# fast-path GEMM epilogues (RW/HG/OUT): bf16 tiles exchanged with v_permlane16_swap so each lane stores 16B (half the store instrs), leaner math, batched sumsq shuffles; compiled epilogue kept as slow p
# speedup vs baseline: 1.0347x; 1.0236x over previous
.LBB0_66:
	ds_read_b128 v[158:161], v164
	ds_read_b128 v[180:183], v165
	ds_read_b128 v[184:187], v166
	ds_read_b128 v[188:191], v167
	s_add_u32 s6, s4, 0xfff7c080
	s_addc_u32 s7, s5, -1
	s_cmp_eq_u32 s53, 28
	s_cselect_b32 s21, s17, s7
	s_cselect_b32 s20, s16, s6
	s_cselect_b32 s7, s19, s23
	s_cselect_b32 s6, s18, s22
	s_mov_b32 m0, s37
	v_lshl_add_u64 v[224:225], s[4:5], 0, v[150:151]
	ds_read_b128 v[192:195], v137
	ds_read_b128 v[196:199], v137 offset:1024
	ds_read_b128 v[200:203], v137 offset:2048
	ds_read_b128 v[204:207], v137 offset:3072
	ds_read_b128 v[208:211], v137 offset:4096
	ds_read_b128 v[212:215], v137 offset:5120
	ds_read_b128 v[216:219], v137 offset:6144
	ds_read_b128 v[220:223], v137 offset:7168
	global_load_lds_dwordx4 v[224:225], off
	v_lshl_add_u64 v[224:225], s[4:5], 0, v[152:153]
	s_mov_b32 m0, s38
	s_nop 0
	global_load_lds_dwordx4 v[224:225], off
	s_waitcnt lgkmcnt(8)
	s_barrier
	s_waitcnt lgkmcnt(0)
	s_setprio 1
	s_waitcnt lgkmcnt(0)
	v_mfma_f32_16x16x32_bf16 v[124:127], v[158:161], v[192:195], v[124:127]
	v_mfma_f32_16x16x32_bf16 v[120:123], v[184:187], v[192:195], v[120:123]
	v_mfma_f32_16x16x32_bf16 v[108:111], v[158:161], v[200:203], v[108:111]
	v_mfma_f32_16x16x32_bf16 v[104:107], v[184:187], v[200:203], v[104:107]
	v_mfma_f32_16x16x32_bf16 v[92:95], v[158:161], v[208:211], v[92:95]
	v_mfma_f32_16x16x32_bf16 v[88:91], v[184:187], v[208:211], v[88:91]
	v_mfma_f32_16x16x32_bf16 v[76:79], v[158:161], v[216:219], v[76:79]
	v_mfma_f32_16x16x32_bf16 v[72:75], v[184:187], v[216:219], v[72:75]
	v_mfma_f32_16x16x32_bf16 v[124:127], v[180:183], v[196:199], v[124:127]
	v_mfma_f32_16x16x32_bf16 v[120:123], v[188:191], v[196:199], v[120:123]
	v_mfma_f32_16x16x32_bf16 v[108:111], v[180:183], v[204:207], v[108:111]
	v_mfma_f32_16x16x32_bf16 v[104:107], v[188:191], v[204:207], v[104:107]
	v_mfma_f32_16x16x32_bf16 v[92:95], v[180:183], v[212:215], v[92:95]
	v_mfma_f32_16x16x32_bf16 v[88:91], v[188:191], v[212:215], v[88:91]
	v_mfma_f32_16x16x32_bf16 v[76:79], v[180:183], v[220:223], v[76:79]
	v_mfma_f32_16x16x32_bf16 v[72:75], v[188:191], v[220:223], v[72:75]
	s_setprio 0
	s_barrier
	s_mov_b32 m0, s28
	v_lshl_add_u64 v[240:241], s[6:7], 0, v[130:131]
	ds_read_b128 v[224:227], v168
	ds_read_b128 v[228:231], v169
	ds_read_b128 v[232:235], v170
	ds_read_b128 v[236:239], v171
	global_load_lds_dwordx4 v[240:241], off
	v_lshl_add_u64 v[242:243], s[6:7], 0, v[132:133]
	s_mov_b32 m0, s29
	s_nop 0
	global_load_lds_dwordx4 v[242:243], off
	s_barrier
	s_waitcnt lgkmcnt(0)
	s_setprio 1
	s_waitcnt lgkmcnt(0)
	v_mfma_f32_16x16x32_bf16 v[116:119], v[224:227], v[192:195], v[116:119]
	v_mfma_f32_16x16x32_bf16 v[112:115], v[232:235], v[192:195], v[112:115]
	v_mfma_f32_16x16x32_bf16 v[100:103], v[224:227], v[200:203], v[100:103]
	v_mfma_f32_16x16x32_bf16 v[96:99], v[232:235], v[200:203], v[96:99]
	v_mfma_f32_16x16x32_bf16 v[84:87], v[224:227], v[208:211], v[84:87]
	v_mfma_f32_16x16x32_bf16 v[80:83], v[232:235], v[208:211], v[80:83]
	v_mfma_f32_16x16x32_bf16 v[68:71], v[224:227], v[216:219], v[68:71]
	v_mfma_f32_16x16x32_bf16 v[64:67], v[232:235], v[216:219], v[64:67]
	v_mfma_f32_16x16x32_bf16 v[116:119], v[228:231], v[196:199], v[116:119]
	v_mfma_f32_16x16x32_bf16 v[112:115], v[236:239], v[196:199], v[112:115]
	v_mfma_f32_16x16x32_bf16 v[100:103], v[228:231], v[204:207], v[100:103]
	v_mfma_f32_16x16x32_bf16 v[96:99], v[236:239], v[204:207], v[96:99]
	v_mfma_f32_16x16x32_bf16 v[84:87], v[228:231], v[212:215], v[84:87]
	v_mfma_f32_16x16x32_bf16 v[80:83], v[236:239], v[212:215], v[80:83]
	v_mfma_f32_16x16x32_bf16 v[68:71], v[228:231], v[220:223], v[68:71]
	v_mfma_f32_16x16x32_bf16 v[64:67], v[236:239], v[220:223], v[64:67]
	s_setprio 0
	s_mov_b32 m0, s40
	v_lshl_add_u64 v[244:245], s[20:21], 0, v[130:131]
	s_barrier
	ds_read_b128 v[192:195], v137 offset:16384
	ds_read_b128 v[196:199], v137 offset:17408
	ds_read_b128 v[200:203], v137 offset:18432
	ds_read_b128 v[204:207], v137 offset:19456
	ds_read_b128 v[208:211], v137 offset:20480
	ds_read_b128 v[212:215], v137 offset:21504
	ds_read_b128 v[216:219], v137 offset:22528
	ds_read_b128 v[220:223], v137 offset:23552
	global_load_lds_dwordx4 v[244:245], off
	v_lshl_add_u64 v[246:247], s[20:21], 0, v[132:133]
	s_mov_b32 m0, s30
	s_nop 0
	global_load_lds_dwordx4 v[246:247], off
	s_barrier
	s_waitcnt lgkmcnt(0)
	s_setprio 1
	s_waitcnt lgkmcnt(0)
	v_mfma_f32_16x16x32_bf16 v[60:63], v[158:161], v[192:195], v[60:63]
	v_mfma_f32_16x16x32_bf16 v[56:59], v[184:187], v[192:195], v[56:59]
	v_mfma_f32_16x16x32_bf16 v[44:47], v[158:161], v[200:203], v[44:47]
	v_mfma_f32_16x16x32_bf16 v[40:43], v[184:187], v[200:203], v[40:43]
	v_mfma_f32_16x16x32_bf16 v[28:31], v[158:161], v[208:211], v[28:31]
	v_mfma_f32_16x16x32_bf16 v[24:27], v[184:187], v[208:211], v[24:27]
	v_mfma_f32_16x16x32_bf16 v[12:15], v[158:161], v[216:219], v[12:15]
	v_mfma_f32_16x16x32_bf16 v[8:11], v[184:187], v[216:219], v[8:11]
	v_mfma_f32_16x16x32_bf16 v[60:63], v[180:183], v[196:199], v[60:63]
	v_mfma_f32_16x16x32_bf16 v[56:59], v[188:191], v[196:199], v[56:59]
	v_mfma_f32_16x16x32_bf16 v[44:47], v[180:183], v[204:207], v[44:47]
	v_mfma_f32_16x16x32_bf16 v[40:43], v[188:191], v[204:207], v[40:43]
	v_mfma_f32_16x16x32_bf16 v[28:31], v[180:183], v[212:215], v[28:31]
	v_mfma_f32_16x16x32_bf16 v[24:27], v[188:191], v[212:215], v[24:27]
	v_mfma_f32_16x16x32_bf16 v[12:15], v[180:183], v[220:223], v[12:15]
	v_mfma_f32_16x16x32_bf16 v[8:11], v[188:191], v[220:223], v[8:11]
	s_setprio 0
	s_barrier
	s_add_u32 s54, s6, 0x84000
	s_addc_u32 s55, s7, 0
	s_mov_b32 m0, s31
	v_lshl_add_u64 v[158:159], s[54:55], 0, v[130:131]
	global_load_lds_dwordx4 v[158:159], off
	v_lshl_add_u64 v[158:159], s[54:55], 0, v[132:133]
	s_mov_b32 m0, s33
	s_nop 0
	global_load_lds_dwordx4 v[158:159], off
	s_waitcnt vmcnt(6)
	s_barrier
	s_setprio 1
	v_mfma_f32_16x16x32_bf16 v[52:55], v[224:227], v[192:195], v[52:55]
	v_mfma_f32_16x16x32_bf16 v[48:51], v[232:235], v[192:195], v[48:51]
	v_mfma_f32_16x16x32_bf16 v[36:39], v[224:227], v[200:203], v[36:39]
	v_mfma_f32_16x16x32_bf16 v[32:35], v[232:235], v[200:203], v[32:35]
	v_mfma_f32_16x16x32_bf16 v[20:23], v[224:227], v[208:211], v[20:23]
	v_mfma_f32_16x16x32_bf16 v[16:19], v[232:235], v[208:211], v[16:19]
	v_mfma_f32_16x16x32_bf16 v[4:7], v[224:227], v[216:219], v[4:7]
	v_mfma_f32_16x16x32_bf16 v[0:3], v[232:235], v[216:219], v[0:3]
	v_mfma_f32_16x16x32_bf16 v[52:55], v[228:231], v[196:199], v[52:55]
	v_mfma_f32_16x16x32_bf16 v[48:51], v[236:239], v[196:199], v[48:51]
	v_mfma_f32_16x16x32_bf16 v[36:39], v[228:231], v[204:207], v[36:39]
	v_mfma_f32_16x16x32_bf16 v[32:35], v[236:239], v[204:207], v[32:35]
	v_mfma_f32_16x16x32_bf16 v[20:23], v[228:231], v[212:215], v[20:23]
	v_mfma_f32_16x16x32_bf16 v[16:19], v[236:239], v[212:215], v[16:19]
	v_mfma_f32_16x16x32_bf16 v[4:7], v[228:231], v[220:223], v[4:7]
	v_mfma_f32_16x16x32_bf16 v[0:3], v[236:239], v[220:223], v[0:3]
	s_setprio 0
	s_barrier
	ds_read_b128 v[158:161], v172
	ds_read_b128 v[180:183], v173
	ds_read_b128 v[184:187], v174
	ds_read_b128 v[188:191], v175
	s_add_u32 s20, s20, 0x84000
	s_addc_u32 s21, s21, 0
	s_mov_b32 m0, s34
	v_lshl_add_u64 v[224:225], s[20:21], 0, v[130:131]
	ds_read_b128 v[192:195], v137 offset:32768
	ds_read_b128 v[196:199], v137 offset:33792
	ds_read_b128 v[200:203], v137 offset:34816
	ds_read_b128 v[204:207], v137 offset:35840
	ds_read_b128 v[208:211], v137 offset:36864
	ds_read_b128 v[212:215], v137 offset:37888
	ds_read_b128 v[216:219], v137 offset:38912
	ds_read_b128 v[220:223], v137 offset:39936
	global_load_lds_dwordx4 v[224:225], off
	v_lshl_add_u64 v[224:225], s[20:21], 0, v[132:133]
	s_mov_b32 m0, s35
	s_nop 0
	global_load_lds_dwordx4 v[224:225], off
	s_waitcnt lgkmcnt(8)
	s_barrier
	s_waitcnt lgkmcnt(0)
	s_setprio 1
	s_waitcnt lgkmcnt(0)
	v_mfma_f32_16x16x32_bf16 v[124:127], v[158:161], v[192:195], v[124:127]
	v_mfma_f32_16x16x32_bf16 v[120:123], v[184:187], v[192:195], v[120:123]
	v_mfma_f32_16x16x32_bf16 v[108:111], v[158:161], v[200:203], v[108:111]
	v_mfma_f32_16x16x32_bf16 v[104:107], v[184:187], v[200:203], v[104:107]
	v_mfma_f32_16x16x32_bf16 v[92:95], v[158:161], v[208:211], v[92:95]
	v_mfma_f32_16x16x32_bf16 v[88:91], v[184:187], v[208:211], v[88:91]
	v_mfma_f32_16x16x32_bf16 v[76:79], v[158:161], v[216:219], v[76:79]
	v_mfma_f32_16x16x32_bf16 v[72:75], v[184:187], v[216:219], v[72:75]
	v_mfma_f32_16x16x32_bf16 v[124:127], v[180:183], v[196:199], v[124:127]
	v_mfma_f32_16x16x32_bf16 v[120:123], v[188:191], v[196:199], v[120:123]
	v_mfma_f32_16x16x32_bf16 v[108:111], v[180:183], v[204:207], v[108:111]
	v_mfma_f32_16x16x32_bf16 v[104:107], v[188:191], v[204:207], v[104:107]
	v_mfma_f32_16x16x32_bf16 v[92:95], v[180:183], v[212:215], v[92:95]
	v_mfma_f32_16x16x32_bf16 v[88:91], v[188:191], v[212:215], v[88:91]
	v_mfma_f32_16x16x32_bf16 v[76:79], v[180:183], v[220:223], v[76:79]
	v_mfma_f32_16x16x32_bf16 v[72:75], v[188:191], v[220:223], v[72:75]
	s_setprio 0
	s_barrier
	s_mov_b32 m0, s47
	v_lshl_add_u64 v[240:241], v[240:241], 0, s[10:11]
	ds_read_b128 v[224:227], v176
	ds_read_b128 v[228:231], v177
	ds_read_b128 v[232:235], v178
	ds_read_b128 v[236:239], v179
	global_load_lds_dwordx4 v[240:241], off
	v_lshl_add_u64 v[240:241], v[242:243], 0, s[10:11]
	s_mov_b32 m0, s48
	s_nop 0
	global_load_lds_dwordx4 v[240:241], off
	s_barrier
	s_waitcnt lgkmcnt(0)
	s_setprio 1
	s_waitcnt lgkmcnt(0)
	v_mfma_f32_16x16x32_bf16 v[116:119], v[224:227], v[192:195], v[116:119]
	v_mfma_f32_16x16x32_bf16 v[112:115], v[232:235], v[192:195], v[112:115]
	v_mfma_f32_16x16x32_bf16 v[100:103], v[224:227], v[200:203], v[100:103]
	v_mfma_f32_16x16x32_bf16 v[96:99], v[232:235], v[200:203], v[96:99]
	v_mfma_f32_16x16x32_bf16 v[84:87], v[224:227], v[208:211], v[84:87]
	v_mfma_f32_16x16x32_bf16 v[80:83], v[232:235], v[208:211], v[80:83]
	v_mfma_f32_16x16x32_bf16 v[68:71], v[224:227], v[216:219], v[68:71]
	v_mfma_f32_16x16x32_bf16 v[64:67], v[232:235], v[216:219], v[64:67]
	v_mfma_f32_16x16x32_bf16 v[116:119], v[228:231], v[196:199], v[116:119]
	v_mfma_f32_16x16x32_bf16 v[112:115], v[236:239], v[196:199], v[112:115]
	v_mfma_f32_16x16x32_bf16 v[100:103], v[228:231], v[204:207], v[100:103]
	v_mfma_f32_16x16x32_bf16 v[96:99], v[236:239], v[204:207], v[96:99]
	v_mfma_f32_16x16x32_bf16 v[84:87], v[228:231], v[212:215], v[84:87]
	v_mfma_f32_16x16x32_bf16 v[80:83], v[236:239], v[212:215], v[80:83]
	v_mfma_f32_16x16x32_bf16 v[68:71], v[228:231], v[220:223], v[68:71]
	v_mfma_f32_16x16x32_bf16 v[64:67], v[236:239], v[220:223], v[64:67]
	s_setprio 0
	s_mov_b32 m0, s49
	v_lshl_add_u64 v[240:241], v[244:245], 0, s[10:11]
	s_barrier
	ds_read_b128 v[192:195], v137 offset:49152
	ds_read_b128 v[196:199], v137 offset:50176
	ds_read_b128 v[200:203], v137 offset:51200
	ds_read_b128 v[204:207], v137 offset:52224
	ds_read_b128 v[208:211], v137 offset:53248
	ds_read_b128 v[212:215], v137 offset:54272
	ds_read_b128 v[216:219], v137 offset:55296
	ds_read_b128 v[220:223], v137 offset:56320
	global_load_lds_dwordx4 v[240:241], off
	v_lshl_add_u64 v[240:241], v[246:247], 0, s[10:11]
	s_mov_b32 m0, s50
	s_nop 0
	global_load_lds_dwordx4 v[240:241], off
	s_barrier
	s_waitcnt lgkmcnt(0)
	s_setprio 1
	s_waitcnt lgkmcnt(0)
	v_mfma_f32_16x16x32_bf16 v[60:63], v[158:161], v[192:195], v[60:63]
	v_mfma_f32_16x16x32_bf16 v[56:59], v[184:187], v[192:195], v[56:59]
	v_mfma_f32_16x16x32_bf16 v[44:47], v[158:161], v[200:203], v[44:47]
	v_mfma_f32_16x16x32_bf16 v[40:43], v[184:187], v[200:203], v[40:43]
	v_mfma_f32_16x16x32_bf16 v[28:31], v[158:161], v[208:211], v[28:31]
	v_mfma_f32_16x16x32_bf16 v[24:27], v[184:187], v[208:211], v[24:27]
	v_mfma_f32_16x16x32_bf16 v[12:15], v[158:161], v[216:219], v[12:15]
	v_mfma_f32_16x16x32_bf16 v[8:11], v[184:187], v[216:219], v[8:11]
	v_mfma_f32_16x16x32_bf16 v[60:63], v[180:183], v[196:199], v[60:63]
	v_mfma_f32_16x16x32_bf16 v[56:59], v[188:191], v[196:199], v[56:59]
	v_mfma_f32_16x16x32_bf16 v[44:47], v[180:183], v[204:207], v[44:47]
	v_mfma_f32_16x16x32_bf16 v[40:43], v[188:191], v[204:207], v[40:43]
	v_mfma_f32_16x16x32_bf16 v[28:31], v[180:183], v[212:215], v[28:31]
	v_mfma_f32_16x16x32_bf16 v[24:27], v[188:191], v[212:215], v[24:27]
	v_mfma_f32_16x16x32_bf16 v[12:15], v[180:183], v[220:223], v[12:15]
	v_mfma_f32_16x16x32_bf16 v[8:11], v[188:191], v[220:223], v[8:11]
	s_setprio 0
	s_barrier
	s_add_u32 s6, s6, 0x84080
	s_addc_u32 s7, s7, 0
	s_mov_b32 m0, s51
	v_lshl_add_u64 v[158:159], s[6:7], 0, v[130:131]
	global_load_lds_dwordx4 v[158:159], off
	v_lshl_add_u64 v[158:159], s[6:7], 0, v[132:133]
	s_mov_b32 m0, s27
	s_nop 0
	global_load_lds_dwordx4 v[158:159], off
	s_waitcnt vmcnt(6)
	s_barrier
	s_setprio 1
	v_mfma_f32_16x16x32_bf16 v[52:55], v[224:227], v[192:195], v[52:55]
	v_mfma_f32_16x16x32_bf16 v[48:51], v[232:235], v[192:195], v[48:51]
	v_mfma_f32_16x16x32_bf16 v[36:39], v[224:227], v[200:203], v[36:39]
	v_mfma_f32_16x16x32_bf16 v[32:35], v[232:235], v[200:203], v[32:35]
	v_mfma_f32_16x16x32_bf16 v[20:23], v[224:227], v[208:211], v[20:23]
	v_mfma_f32_16x16x32_bf16 v[16:19], v[232:235], v[208:211], v[16:19]
	v_mfma_f32_16x16x32_bf16 v[4:7], v[224:227], v[216:219], v[4:7]
	v_mfma_f32_16x16x32_bf16 v[0:3], v[232:235], v[216:219], v[0:3]
	v_mfma_f32_16x16x32_bf16 v[52:55], v[228:231], v[196:199], v[52:55]
	v_mfma_f32_16x16x32_bf16 v[48:51], v[236:239], v[196:199], v[48:51]
	v_mfma_f32_16x16x32_bf16 v[36:39], v[228:231], v[204:207], v[36:39]
	v_mfma_f32_16x16x32_bf16 v[32:35], v[236:239], v[204:207], v[32:35]
	v_mfma_f32_16x16x32_bf16 v[20:23], v[228:231], v[212:215], v[20:23]
	v_mfma_f32_16x16x32_bf16 v[16:19], v[236:239], v[212:215], v[16:19]
	v_mfma_f32_16x16x32_bf16 v[4:7], v[228:231], v[220:223], v[4:7]
	v_mfma_f32_16x16x32_bf16 v[0:3], v[236:239], v[220:223], v[0:3]
	s_setprio 0
	s_add_i32 s53, s53, 2
	s_add_u32 s4, s4, 0x100
	s_addc_u32 s5, s5, 0
	s_add_u32 s22, s22, 0x100
	s_addc_u32 s23, s23, 0
	s_cmp_gt_u32 s53, 29
	s_barrier
	s_cbranch_scc0 .LBB0_66
	s_cmp_lt_u32 s43, 0x80
	s_cbranch_scc0 .Lepi_rw_slow
	s_cmp_eq_u32 s43, 64
	s_cbranch_scc1 .Lepi_rw_slow
	s_cmp_eq_u32 s24, 0
	s_cbranch_scc1 .Lepi_rw_slow
	s_lshl_b32 s4, s43, 8
	s_add_i32 s4, s4, s46
	v_or_b32_e32 v180, s4, v134
	v_mad_i64_i32 v[160:161], s[6:7], v180, s41, 0
	v_lshrrev_b32_e32 v181, 2, v145
	v_and_b32_e32 v182, 1, v181
	v_bfe_u32 v183, v181, 1, 1
	v_and_b32_e32 v181, 0x60, v145
	v_lshlrev_b32_e32 v181, 1, v181
	v_lshl_add_u32 v181, v182, 5, v181
	v_lshl_add_u32 v181, v183, 4, v181
	s_lshl_b32 s5, s24, 9
	s_sub_i32 s5, s5, 0x100
	v_add_u32_e32 v181, s5, v181
	v_lshl_add_u64 v[160:161], s[72:73], 0, v[160:161]
	v_add_co_u32_e32 v184, vcc, v160, v181
	s_mov_b32 s20, 0x21000
	s_mov_b32 s21, 0
	v_addc_co_u32_e32 v185, vcc, 0, v161, vcc
	s_mov_b32 s22, 0xa5000
	s_mov_b32 s23, 0
	v_cvt_pk_bf16_f32 v192, v124, v125
	v_cvt_pk_bf16_f32 v193, v126, v127
	v_cvt_pk_bf16_f32 v194, v120, v121
	v_cvt_pk_bf16_f32 v195, v122, v123
	v_cvt_pk_bf16_f32 v196, v116, v117
	v_cvt_pk_bf16_f32 v197, v118, v119
	v_cvt_pk_bf16_f32 v198, v112, v113
	v_cvt_pk_bf16_f32 v199, v114, v115
	s_nop 0
	v_permlane16_swap_b32_e32 v192, v194
	v_permlane16_swap_b32_e32 v193, v195
	v_permlane16_swap_b32_e32 v196, v198
	v_permlane16_swap_b32_e32 v197, v199
	s_nop 0
	global_store_dwordx4 v[184:185], v[192:195], off
	global_store_dwordx4 v[184:185], v[196:199], off offset:256
	v_lshl_add_u64 v[184:185], v[184:185], 0, s[20:21]
	v_cvt_pk_bf16_f32 v200, v108, v109
	v_cvt_pk_bf16_f32 v201, v110, v111
	v_cvt_pk_bf16_f32 v202, v104, v105
	v_cvt_pk_bf16_f32 v203, v106, v107
	v_cvt_pk_bf16_f32 v204, v100, v101
	v_cvt_pk_bf16_f32 v205, v102, v103
	v_cvt_pk_bf16_f32 v206, v96, v97
	v_cvt_pk_bf16_f32 v207, v98, v99
	s_nop 0
	v_permlane16_swap_b32_e32 v200, v202
	v_permlane16_swap_b32_e32 v201, v203
	v_permlane16_swap_b32_e32 v204, v206
	v_permlane16_swap_b32_e32 v205, v207
	s_nop 0
	global_store_dwordx4 v[184:185], v[200:203], off
	global_store_dwordx4 v[184:185], v[204:207], off offset:256
	v_lshl_add_u64 v[184:185], v[184:185], 0, s[20:21]
	v_cvt_pk_bf16_f32 v208, v92, v93
	v_cvt_pk_bf16_f32 v209, v94, v95
	v_cvt_pk_bf16_f32 v210, v88, v89
	v_cvt_pk_bf16_f32 v211, v90, v91
	v_cvt_pk_bf16_f32 v212, v84, v85
	v_cvt_pk_bf16_f32 v213, v86, v87
	v_cvt_pk_bf16_f32 v214, v80, v81
	v_cvt_pk_bf16_f32 v215, v82, v83
	s_nop 0
	v_permlane16_swap_b32_e32 v208, v210
	v_permlane16_swap_b32_e32 v209, v211
	v_permlane16_swap_b32_e32 v212, v214
	v_permlane16_swap_b32_e32 v213, v215
	s_nop 0
	global_store_dwordx4 v[184:185], v[208:211], off
	global_store_dwordx4 v[184:185], v[212:215], off offset:256
	v_lshl_add_u64 v[184:185], v[184:185], 0, s[20:21]
	v_cvt_pk_bf16_f32 v216, v76, v77
	v_cvt_pk_bf16_f32 v217, v78, v79
	v_cvt_pk_bf16_f32 v218, v72, v73
	v_cvt_pk_bf16_f32 v219, v74, v75
	v_cvt_pk_bf16_f32 v220, v68, v69
	v_cvt_pk_bf16_f32 v221, v70, v71
	v_cvt_pk_bf16_f32 v222, v64, v65
	v_cvt_pk_bf16_f32 v223, v66, v67
	s_nop 0
	v_permlane16_swap_b32_e32 v216, v218
	v_permlane16_swap_b32_e32 v217, v219
	v_permlane16_swap_b32_e32 v220, v222
	v_permlane16_swap_b32_e32 v221, v223
	s_nop 0
	global_store_dwordx4 v[184:185], v[216:219], off
	global_store_dwordx4 v[184:185], v[220:223], off offset:256
	v_lshl_add_u64 v[184:185], v[184:185], 0, s[22:23]
	v_cvt_pk_bf16_f32 v192, v60, v61
	v_cvt_pk_bf16_f32 v193, v62, v63
	v_cvt_pk_bf16_f32 v194, v56, v57
	v_cvt_pk_bf16_f32 v195, v58, v59
	v_cvt_pk_bf16_f32 v196, v52, v53
	v_cvt_pk_bf16_f32 v197, v54, v55
	v_cvt_pk_bf16_f32 v198, v48, v49
	v_cvt_pk_bf16_f32 v199, v50, v51
	s_nop 0
	v_permlane16_swap_b32_e32 v192, v194
	v_permlane16_swap_b32_e32 v193, v195
	v_permlane16_swap_b32_e32 v196, v198
	v_permlane16_swap_b32_e32 v197, v199
	s_nop 0
	global_store_dwordx4 v[184:185], v[192:195], off
	global_store_dwordx4 v[184:185], v[196:199], off offset:256
	v_lshl_add_u64 v[184:185], v[184:185], 0, s[20:21]
	v_cvt_pk_bf16_f32 v200, v44, v45
	v_cvt_pk_bf16_f32 v201, v46, v47
	v_cvt_pk_bf16_f32 v202, v40, v41
	v_cvt_pk_bf16_f32 v203, v42, v43
	v_cvt_pk_bf16_f32 v204, v36, v37
	v_cvt_pk_bf16_f32 v205, v38, v39
	v_cvt_pk_bf16_f32 v206, v32, v33
	v_cvt_pk_bf16_f32 v207, v34, v35
	s_nop 0
	v_permlane16_swap_b32_e32 v200, v202
	v_permlane16_swap_b32_e32 v201, v203
	v_permlane16_swap_b32_e32 v204, v206
	v_permlane16_swap_b32_e32 v205, v207
	s_nop 0
	global_store_dwordx4 v[184:185], v[200:203], off
	global_store_dwordx4 v[184:185], v[204:207], off offset:256
	v_lshl_add_u64 v[184:185], v[184:185], 0, s[20:21]
	v_cvt_pk_bf16_f32 v208, v28, v29
	v_cvt_pk_bf16_f32 v209, v30, v31
	v_cvt_pk_bf16_f32 v210, v24, v25
	v_cvt_pk_bf16_f32 v211, v26, v27
	v_cvt_pk_bf16_f32 v212, v20, v21
	v_cvt_pk_bf16_f32 v213, v22, v23
	v_cvt_pk_bf16_f32 v214, v16, v17
	v_cvt_pk_bf16_f32 v215, v18, v19
	s_nop 0
	v_permlane16_swap_b32_e32 v208, v210
	v_permlane16_swap_b32_e32 v209, v211
	v_permlane16_swap_b32_e32 v212, v214
	v_permlane16_swap_b32_e32 v213, v215
	s_nop 0
	global_store_dwordx4 v[184:185], v[208:211], off
	global_store_dwordx4 v[184:185], v[212:215], off offset:256
	v_lshl_add_u64 v[184:185], v[184:185], 0, s[20:21]
	v_cvt_pk_bf16_f32 v216, v12, v13
	v_cvt_pk_bf16_f32 v217, v14, v15
	v_cvt_pk_bf16_f32 v218, v8, v9
	v_cvt_pk_bf16_f32 v219, v10, v11
	v_cvt_pk_bf16_f32 v220, v4, v5
	v_cvt_pk_bf16_f32 v221, v6, v7
	v_cvt_pk_bf16_f32 v222, v0, v1
	v_cvt_pk_bf16_f32 v223, v2, v3
	s_nop 0
	v_permlane16_swap_b32_e32 v216, v218
	v_permlane16_swap_b32_e32 v217, v219
	v_permlane16_swap_b32_e32 v220, v222
	v_permlane16_swap_b32_e32 v221, v223
	s_nop 0
	global_store_dwordx4 v[184:185], v[216:219], off
	global_store_dwordx4 v[184:185], v[220:223], off offset:256
	s_branch .LBB0_54
.Lepi_rw_slow:
	s_lshl_b32 s43, s43, 8
	s_add_i32 s43, s43, s46
	v_or_b32_e32 v180, s43, v134
	v_lshl_or_b32 v158, s24, 8, v145
	v_cmp_gt_i32_e32 vcc, s39, v180
	s_and_saveexec_b64 s[20:21], vcc
	s_cbranch_execz .LBB0_79
	v_mad_i64_i32 v[160:161], s[6:7], v180, s41, 0
	v_cmp_eq_u32_e64 s[4:5], s56, v180
	v_cmp_ne_u32_e32 vcc, s56, v180
	v_cmp_lt_i32_e64 s[6:7], s42, v158
	v_lshl_add_u64 v[160:161], s[72:73], 0, v[160:161]
	s_and_saveexec_b64 s[22:23], s[6:7]
	s_cbranch_execz .LBB0_71
	v_add_u32_e32 v148, 0xffffff80, v158
	v_cvt_pk_bf16_f32 v182, v124, v125
	v_cvt_pk_bf16_f32 v183, v126, v127
	v_lshl_add_u64 v[184:185], v[148:149], 1, v[160:161]
	global_store_dwordx2 v[184:185], v[182:183], off
	s_and_b64 exec, exec, s[4:5]
	s_cbranch_execz .LBB0_71
	v_lshl_add_u64 v[182:183], v[148:149], 2, s[12:13]
	global_store_dwordx4 v[182:183], v[124:127], off

.LBB0_232:
	ds_read_b128 v[156:159], v167
	ds_read_b128 v[186:189], v168
	ds_read_b128 v[190:193], v169
	ds_read_b128 v[194:197], v170
	s_add_u32 s6, s4, 0xfff7c080
	s_addc_u32 s7, s5, -1
	s_cmp_eq_u32 s21, 28
	s_cselect_b32 s17, s13, s7
	s_cselect_b32 s16, s12, s6
	s_cselect_b32 s7, s15, s19
	s_cselect_b32 s6, s14, s18
	s_mov_b32 m0, s51
	v_lshl_add_u64 v[160:161], s[4:5], 0, v[148:149]
	ds_read_b128 v[198:201], v165
	ds_read_b128 v[202:205], v165 offset:1024
	ds_read_b128 v[206:209], v165 offset:2048
	ds_read_b128 v[210:213], v165 offset:3072
	ds_read_b128 v[214:217], v165 offset:4096
	ds_read_b128 v[218:221], v165 offset:5120
	ds_read_b128 v[222:225], v165 offset:6144
	ds_read_b128 v[226:229], v165 offset:7168
	global_load_lds_dwordx4 v[160:161], off
	v_lshl_add_u64 v[160:161], s[4:5], 0, v[150:151]
	s_mov_b32 m0, s38
	s_nop 0
	global_load_lds_dwordx4 v[160:161], off
	s_waitcnt lgkmcnt(8)
	s_barrier
	s_waitcnt lgkmcnt(0)
	s_setprio 1
	s_waitcnt lgkmcnt(0)
	v_mfma_f32_16x16x32_bf16 v[124:127], v[156:159], v[198:201], v[124:127]
	v_mfma_f32_16x16x32_bf16 v[120:123], v[190:193], v[198:201], v[120:123]
	v_mfma_f32_16x16x32_bf16 v[108:111], v[156:159], v[206:209], v[108:111]
	v_mfma_f32_16x16x32_bf16 v[104:107], v[190:193], v[206:209], v[104:107]
	v_mfma_f32_16x16x32_bf16 v[92:95], v[156:159], v[214:217], v[92:95]
	v_mfma_f32_16x16x32_bf16 v[88:91], v[190:193], v[214:217], v[88:91]
	v_mfma_f32_16x16x32_bf16 v[76:79], v[156:159], v[222:225], v[76:79]
	v_mfma_f32_16x16x32_bf16 v[72:75], v[190:193], v[222:225], v[72:75]
	v_mfma_f32_16x16x32_bf16 v[124:127], v[186:189], v[202:205], v[124:127]
	v_mfma_f32_16x16x32_bf16 v[120:123], v[194:197], v[202:205], v[120:123]
	v_mfma_f32_16x16x32_bf16 v[108:111], v[186:189], v[210:213], v[108:111]
	v_mfma_f32_16x16x32_bf16 v[104:107], v[194:197], v[210:213], v[104:107]
	v_mfma_f32_16x16x32_bf16 v[92:95], v[186:189], v[218:221], v[92:95]
	v_mfma_f32_16x16x32_bf16 v[88:91], v[194:197], v[218:221], v[88:91]
	v_mfma_f32_16x16x32_bf16 v[76:79], v[186:189], v[226:229], v[76:79]
	v_mfma_f32_16x16x32_bf16 v[72:75], v[194:197], v[226:229], v[72:75]
	s_setprio 0
	s_barrier
	s_mov_b32 m0, s24
	v_lshl_add_u64 v[160:161], s[6:7], 0, v[130:131]
	ds_read_b128 v[230:233], v171
	ds_read_b128 v[234:237], v172
	ds_read_b128 v[238:241], v173
	ds_read_b128 v[242:245], v174
	global_load_lds_dwordx4 v[160:161], off
	v_lshl_add_u64 v[246:247], s[6:7], 0, v[132:133]
	s_mov_b32 m0, s25
	s_nop 0
	global_load_lds_dwordx4 v[246:247], off
	s_barrier
	s_waitcnt lgkmcnt(0)
	s_setprio 1
	s_waitcnt lgkmcnt(0)
	v_mfma_f32_16x16x32_bf16 v[116:119], v[230:233], v[198:201], v[116:119]
	v_mfma_f32_16x16x32_bf16 v[112:115], v[238:241], v[198:201], v[112:115]
	v_mfma_f32_16x16x32_bf16 v[100:103], v[230:233], v[206:209], v[100:103]
	v_mfma_f32_16x16x32_bf16 v[96:99], v[238:241], v[206:209], v[96:99]
	v_mfma_f32_16x16x32_bf16 v[84:87], v[230:233], v[214:217], v[84:87]
	v_mfma_f32_16x16x32_bf16 v[80:83], v[238:241], v[214:217], v[80:83]
	v_mfma_f32_16x16x32_bf16 v[68:71], v[230:233], v[222:225], v[68:71]
	v_mfma_f32_16x16x32_bf16 v[64:67], v[238:241], v[222:225], v[64:67]
	v_mfma_f32_16x16x32_bf16 v[116:119], v[234:237], v[202:205], v[116:119]
	v_mfma_f32_16x16x32_bf16 v[112:115], v[242:245], v[202:205], v[112:115]
	v_mfma_f32_16x16x32_bf16 v[100:103], v[234:237], v[210:213], v[100:103]
	v_mfma_f32_16x16x32_bf16 v[96:99], v[242:245], v[210:213], v[96:99]
	v_mfma_f32_16x16x32_bf16 v[84:87], v[234:237], v[218:221], v[84:87]
	v_mfma_f32_16x16x32_bf16 v[80:83], v[242:245], v[218:221], v[80:83]
	v_mfma_f32_16x16x32_bf16 v[68:71], v[234:237], v[226:229], v[68:71]
	v_mfma_f32_16x16x32_bf16 v[64:67], v[242:245], v[226:229], v[64:67]
	s_setprio 0
	s_mov_b32 m0, s23
	v_lshl_add_u64 v[248:249], s[16:17], 0, v[130:131]
	s_barrier
	ds_read_b128 v[198:201], v165 offset:16384
	ds_read_b128 v[202:205], v165 offset:17408
	ds_read_b128 v[206:209], v165 offset:18432
	ds_read_b128 v[210:213], v165 offset:19456
	ds_read_b128 v[214:217], v165 offset:20480
	ds_read_b128 v[218:221], v165 offset:21504
	ds_read_b128 v[222:225], v165 offset:22528
	ds_read_b128 v[226:229], v165 offset:23552
	global_load_lds_dwordx4 v[248:249], off
	v_lshl_add_u64 v[250:251], s[16:17], 0, v[132:133]
	s_mov_b32 m0, s26
	s_nop 0
	global_load_lds_dwordx4 v[250:251], off
	s_barrier
	s_waitcnt lgkmcnt(0)
	s_setprio 1
	s_waitcnt lgkmcnt(0)
	v_mfma_f32_16x16x32_bf16 v[60:63], v[156:159], v[198:201], v[60:63]
	v_mfma_f32_16x16x32_bf16 v[56:59], v[190:193], v[198:201], v[56:59]
	v_mfma_f32_16x16x32_bf16 v[44:47], v[156:159], v[206:209], v[44:47]
	v_mfma_f32_16x16x32_bf16 v[40:43], v[190:193], v[206:209], v[40:43]
	v_mfma_f32_16x16x32_bf16 v[28:31], v[156:159], v[214:217], v[28:31]
	v_mfma_f32_16x16x32_bf16 v[24:27], v[190:193], v[214:217], v[24:27]
	v_mfma_f32_16x16x32_bf16 v[12:15], v[156:159], v[222:225], v[12:15]
	v_mfma_f32_16x16x32_bf16 v[8:11], v[190:193], v[222:225], v[8:11]
	v_mfma_f32_16x16x32_bf16 v[60:63], v[186:189], v[202:205], v[60:63]
	v_mfma_f32_16x16x32_bf16 v[56:59], v[194:197], v[202:205], v[56:59]
	v_mfma_f32_16x16x32_bf16 v[44:47], v[186:189], v[210:213], v[44:47]
	v_mfma_f32_16x16x32_bf16 v[40:43], v[194:197], v[210:213], v[40:43]
	v_mfma_f32_16x16x32_bf16 v[28:31], v[186:189], v[218:221], v[28:31]
	v_mfma_f32_16x16x32_bf16 v[24:27], v[194:197], v[218:221], v[24:27]
	v_mfma_f32_16x16x32_bf16 v[12:15], v[186:189], v[226:229], v[12:15]
	v_mfma_f32_16x16x32_bf16 v[8:11], v[194:197], v[226:229], v[8:11]
	s_setprio 0
	s_barrier
	s_add_u32 s36, s6, 0x84000
	s_addc_u32 s37, s7, 0
	s_mov_b32 m0, s27
	v_lshl_add_u64 v[156:157], s[36:37], 0, v[130:131]
	global_load_lds_dwordx4 v[156:157], off
	v_lshl_add_u64 v[156:157], s[36:37], 0, v[132:133]
	s_mov_b32 m0, s28
	s_nop 0
	global_load_lds_dwordx4 v[156:157], off
	s_waitcnt vmcnt(6)
	s_barrier
	s_setprio 1
	v_mfma_f32_16x16x32_bf16 v[52:55], v[230:233], v[198:201], v[52:55]
	v_mfma_f32_16x16x32_bf16 v[48:51], v[238:241], v[198:201], v[48:51]
	v_mfma_f32_16x16x32_bf16 v[36:39], v[230:233], v[206:209], v[36:39]
	v_mfma_f32_16x16x32_bf16 v[32:35], v[238:241], v[206:209], v[32:35]
	v_mfma_f32_16x16x32_bf16 v[20:23], v[230:233], v[214:217], v[20:23]
	v_mfma_f32_16x16x32_bf16 v[16:19], v[238:241], v[214:217], v[16:19]
	v_mfma_f32_16x16x32_bf16 v[4:7], v[230:233], v[222:225], v[4:7]
	v_mfma_f32_16x16x32_bf16 v[0:3], v[238:241], v[222:225], v[0:3]
	v_mfma_f32_16x16x32_bf16 v[52:55], v[234:237], v[202:205], v[52:55]
	v_mfma_f32_16x16x32_bf16 v[48:51], v[242:245], v[202:205], v[48:51]
	v_mfma_f32_16x16x32_bf16 v[36:39], v[234:237], v[210:213], v[36:39]
	v_mfma_f32_16x16x32_bf16 v[32:35], v[242:245], v[210:213], v[32:35]
	v_mfma_f32_16x16x32_bf16 v[20:23], v[234:237], v[218:221], v[20:23]
	v_mfma_f32_16x16x32_bf16 v[16:19], v[242:245], v[218:221], v[16:19]
	v_mfma_f32_16x16x32_bf16 v[4:7], v[234:237], v[226:229], v[4:7]
	v_mfma_f32_16x16x32_bf16 v[0:3], v[242:245], v[226:229], v[0:3]
	s_setprio 0
	s_barrier
	ds_read_b128 v[156:159], v175
	ds_read_b128 v[186:189], v176
	ds_read_b128 v[190:193], v177
	ds_read_b128 v[194:197], v178
	s_add_u32 s16, s16, 0x84000
	s_addc_u32 s17, s17, 0
	s_mov_b32 m0, s29
	v_lshl_add_u64 v[230:231], s[16:17], 0, v[130:131]
	ds_read_b128 v[198:201], v165 offset:32768
	ds_read_b128 v[202:205], v165 offset:33792
	ds_read_b128 v[206:209], v165 offset:34816
	ds_read_b128 v[210:213], v165 offset:35840
	ds_read_b128 v[214:217], v165 offset:36864
	ds_read_b128 v[218:221], v165 offset:37888
	ds_read_b128 v[222:225], v165 offset:38912
	ds_read_b128 v[226:229], v165 offset:39936
	global_load_lds_dwordx4 v[230:231], off
	v_lshl_add_u64 v[230:231], s[16:17], 0, v[132:133]
	s_mov_b32 m0, s30
	s_nop 0
	global_load_lds_dwordx4 v[230:231], off
	s_waitcnt lgkmcnt(8)
	s_barrier
	s_waitcnt lgkmcnt(0)
	s_setprio 1
	s_waitcnt lgkmcnt(0)
	v_mfma_f32_16x16x32_bf16 v[124:127], v[156:159], v[198:201], v[124:127]
	v_mfma_f32_16x16x32_bf16 v[120:123], v[190:193], v[198:201], v[120:123]
	v_mfma_f32_16x16x32_bf16 v[108:111], v[156:159], v[206:209], v[108:111]
	v_mfma_f32_16x16x32_bf16 v[104:107], v[190:193], v[206:209], v[104:107]
	v_mfma_f32_16x16x32_bf16 v[92:95], v[156:159], v[214:217], v[92:95]
	v_mfma_f32_16x16x32_bf16 v[88:91], v[190:193], v[214:217], v[88:91]
	v_mfma_f32_16x16x32_bf16 v[76:79], v[156:159], v[222:225], v[76:79]
	v_mfma_f32_16x16x32_bf16 v[72:75], v[190:193], v[222:225], v[72:75]
	v_mfma_f32_16x16x32_bf16 v[124:127], v[186:189], v[202:205], v[124:127]
	v_mfma_f32_16x16x32_bf16 v[120:123], v[194:197], v[202:205], v[120:123]
	v_mfma_f32_16x16x32_bf16 v[108:111], v[186:189], v[210:213], v[108:111]
	v_mfma_f32_16x16x32_bf16 v[104:107], v[194:197], v[210:213], v[104:107]
	v_mfma_f32_16x16x32_bf16 v[92:95], v[186:189], v[218:221], v[92:95]
	v_mfma_f32_16x16x32_bf16 v[88:91], v[194:197], v[218:221], v[88:91]
	v_mfma_f32_16x16x32_bf16 v[76:79], v[186:189], v[226:229], v[76:79]
	v_mfma_f32_16x16x32_bf16 v[72:75], v[194:197], v[226:229], v[72:75]
	s_setprio 0
	s_barrier
	s_mov_b32 m0, s31
	v_lshl_add_u64 v[160:161], v[160:161], 0, s[10:11]
	ds_read_b128 v[230:233], v179
	ds_read_b128 v[234:237], v180
	ds_read_b128 v[238:241], v181
	ds_read_b128 v[242:245], v182
	global_load_lds_dwordx4 v[160:161], off
	v_lshl_add_u64 v[160:161], v[246:247], 0, s[10:11]
	s_mov_b32 m0, s34
	s_nop 0
	global_load_lds_dwordx4 v[160:161], off
	s_barrier
	s_waitcnt lgkmcnt(0)
	s_setprio 1
	s_waitcnt lgkmcnt(0)
	v_mfma_f32_16x16x32_bf16 v[116:119], v[230:233], v[198:201], v[116:119]
	v_mfma_f32_16x16x32_bf16 v[112:115], v[238:241], v[198:201], v[112:115]
	v_mfma_f32_16x16x32_bf16 v[100:103], v[230:233], v[206:209], v[100:103]
	v_mfma_f32_16x16x32_bf16 v[96:99], v[238:241], v[206:209], v[96:99]
	v_mfma_f32_16x16x32_bf16 v[84:87], v[230:233], v[214:217], v[84:87]
	v_mfma_f32_16x16x32_bf16 v[80:83], v[238:241], v[214:217], v[80:83]
	v_mfma_f32_16x16x32_bf16 v[68:71], v[230:233], v[222:225], v[68:71]
	v_mfma_f32_16x16x32_bf16 v[64:67], v[238:241], v[222:225], v[64:67]
	v_mfma_f32_16x16x32_bf16 v[116:119], v[234:237], v[202:205], v[116:119]
	v_mfma_f32_16x16x32_bf16 v[112:115], v[242:245], v[202:205], v[112:115]
	v_mfma_f32_16x16x32_bf16 v[100:103], v[234:237], v[210:213], v[100:103]
	v_mfma_f32_16x16x32_bf16 v[96:99], v[242:245], v[210:213], v[96:99]
	v_mfma_f32_16x16x32_bf16 v[84:87], v[234:237], v[218:221], v[84:87]
	v_mfma_f32_16x16x32_bf16 v[80:83], v[242:245], v[218:221], v[80:83]
	v_mfma_f32_16x16x32_bf16 v[68:71], v[234:237], v[226:229], v[68:71]
	v_mfma_f32_16x16x32_bf16 v[64:67], v[242:245], v[226:229], v[64:67]
	s_setprio 0
	s_mov_b32 m0, s35
	v_lshl_add_u64 v[160:161], v[248:249], 0, s[10:11]
	s_barrier
	ds_read_b128 v[198:201], v165 offset:49152
	ds_read_b128 v[202:205], v165 offset:50176
	ds_read_b128 v[206:209], v165 offset:51200
	ds_read_b128 v[210:213], v165 offset:52224
	ds_read_b128 v[214:217], v165 offset:53248
	ds_read_b128 v[218:221], v165 offset:54272
	ds_read_b128 v[222:225], v165 offset:55296
	ds_read_b128 v[226:229], v165 offset:56320
	global_load_lds_dwordx4 v[160:161], off
	v_lshl_add_u64 v[160:161], v[250:251], 0, s[10:11]
	s_mov_b32 m0, s44
	s_nop 0
	global_load_lds_dwordx4 v[160:161], off
	s_barrier
	s_waitcnt lgkmcnt(0)
	s_setprio 1
	s_waitcnt lgkmcnt(0)
	v_mfma_f32_16x16x32_bf16 v[60:63], v[156:159], v[198:201], v[60:63]
	v_mfma_f32_16x16x32_bf16 v[56:59], v[190:193], v[198:201], v[56:59]
	v_mfma_f32_16x16x32_bf16 v[44:47], v[156:159], v[206:209], v[44:47]
	v_mfma_f32_16x16x32_bf16 v[40:43], v[190:193], v[206:209], v[40:43]
	v_mfma_f32_16x16x32_bf16 v[28:31], v[156:159], v[214:217], v[28:31]
	v_mfma_f32_16x16x32_bf16 v[24:27], v[190:193], v[214:217], v[24:27]
	v_mfma_f32_16x16x32_bf16 v[12:15], v[156:159], v[222:225], v[12:15]
	v_mfma_f32_16x16x32_bf16 v[8:11], v[190:193], v[222:225], v[8:11]
	v_mfma_f32_16x16x32_bf16 v[60:63], v[186:189], v[202:205], v[60:63]
	v_mfma_f32_16x16x32_bf16 v[56:59], v[194:197], v[202:205], v[56:59]
	v_mfma_f32_16x16x32_bf16 v[44:47], v[186:189], v[210:213], v[44:47]
	v_mfma_f32_16x16x32_bf16 v[40:43], v[194:197], v[210:213], v[40:43]
	v_mfma_f32_16x16x32_bf16 v[28:31], v[186:189], v[218:221], v[28:31]
	v_mfma_f32_16x16x32_bf16 v[24:27], v[194:197], v[218:221], v[24:27]
	v_mfma_f32_16x16x32_bf16 v[12:15], v[186:189], v[226:229], v[12:15]
	v_mfma_f32_16x16x32_bf16 v[8:11], v[194:197], v[226:229], v[8:11]
	s_setprio 0
	s_barrier
	s_add_u32 s6, s6, 0x84080
	s_addc_u32 s7, s7, 0
	s_mov_b32 m0, s45
	v_lshl_add_u64 v[156:157], s[6:7], 0, v[130:131]
	global_load_lds_dwordx4 v[156:157], off
	v_lshl_add_u64 v[156:157], s[6:7], 0, v[132:133]
	s_mov_b32 m0, s46
	s_nop 0
	global_load_lds_dwordx4 v[156:157], off
	s_waitcnt vmcnt(6)
	s_barrier
	s_setprio 1
	v_mfma_f32_16x16x32_bf16 v[52:55], v[230:233], v[198:201], v[52:55]
	v_mfma_f32_16x16x32_bf16 v[48:51], v[238:241], v[198:201], v[48:51]
	v_mfma_f32_16x16x32_bf16 v[36:39], v[230:233], v[206:209], v[36:39]
	v_mfma_f32_16x16x32_bf16 v[32:35], v[238:241], v[206:209], v[32:35]
	v_mfma_f32_16x16x32_bf16 v[20:23], v[230:233], v[214:217], v[20:23]
	v_mfma_f32_16x16x32_bf16 v[16:19], v[238:241], v[214:217], v[16:19]
	v_mfma_f32_16x16x32_bf16 v[4:7], v[230:233], v[222:225], v[4:7]
	v_mfma_f32_16x16x32_bf16 v[0:3], v[238:241], v[222:225], v[0:3]
	v_mfma_f32_16x16x32_bf16 v[52:55], v[234:237], v[202:205], v[52:55]
	v_mfma_f32_16x16x32_bf16 v[48:51], v[242:245], v[202:205], v[48:51]
	v_mfma_f32_16x16x32_bf16 v[36:39], v[234:237], v[210:213], v[36:39]
	v_mfma_f32_16x16x32_bf16 v[32:35], v[242:245], v[210:213], v[32:35]
	v_mfma_f32_16x16x32_bf16 v[20:23], v[234:237], v[218:221], v[20:23]
	v_mfma_f32_16x16x32_bf16 v[16:19], v[242:245], v[218:221], v[16:19]
	v_mfma_f32_16x16x32_bf16 v[4:7], v[234:237], v[226:229], v[4:7]
	v_mfma_f32_16x16x32_bf16 v[0:3], v[242:245], v[226:229], v[0:3]
	s_setprio 0
	s_add_i32 s21, s21, 2
	s_add_u32 s4, s4, 0x100
	s_addc_u32 s5, s5, 0
	s_add_u32 s18, s18, 0x100
	s_addc_u32 s19, s19, 0
	s_cmp_gt_u32 s21, 29
	s_barrier
	s_cbranch_scc0 .LBB0_232
	s_cmp_lt_u32 s20, 0x88
	s_cbranch_scc0 .Lepi_hg_slow
	v_lshl_add_u32 v160, s20, 8, v143
	v_mov_b64_e32 v[156:157], s[72:73]
	v_mad_i64_i32 v[158:159], s[4:5], v160, s40, v[156:157]
	v_lshrrev_b32_e32 v160, 2, v166
	v_and_b32_e32 v161, 1, v160
	v_bfe_u32 v186, v160, 1, 1
	v_and_b32_e32 v160, 0x60, v166
	v_lshlrev_b32_e32 v160, 1, v160
	v_lshl_add_u32 v160, v161, 5, v160
	v_lshl_add_u32 v160, v186, 4, v160
	s_lshl_b32 s5, s2, 9
	v_add_u32_e32 v160, s5, v160
	s_mov_b32 s16, 0x20800
	v_add_co_u32_e32 v158, vcc, v158, v160
	s_mov_b32 s17, 0
	s_mov_b32 s18, 0xa2800
	v_addc_co_u32_e32 v159, vcc, 0, v159, vcc
	s_mov_b32 s19, 0
	s_lshr_b32 s4, s2, 2
	s_cmp_eq_u32 s4, 2
	s_cbranch_scc1 .Lepi_hg_copy
	s_cmp_eq_u32 s4, 1
	s_cbranch_scc1 .Lepi_hg_forget
	v_mul_f32_e32 v186, 0xbfb8aa3b, v124
	v_mul_f32_e32 v187, 0xbfb8aa3b, v125
	v_mul_f32_e32 v188, 0xbfb8aa3b, v126
	v_mul_f32_e32 v189, 0xbfb8aa3b, v127
	v_mul_f32_e32 v190, 0xbfb8aa3b, v120
	v_mul_f32_e32 v191, 0xbfb8aa3b, v121
	v_mul_f32_e32 v192, 0xbfb8aa3b, v122
	v_mul_f32_e32 v193, 0xbfb8aa3b, v123
	v_exp_f32_e32 v186, v186
	v_exp_f32_e32 v187, v187
	v_exp_f32_e32 v188, v188
	v_exp_f32_e32 v189, v189
	v_exp_f32_e32 v190, v190
	v_exp_f32_e32 v191, v191
	v_exp_f32_e32 v192, v192
	v_exp_f32_e32 v193, v193
	v_add_f32_e32 v186, 1.0, v186
	v_add_f32_e32 v187, 1.0, v187
	v_add_f32_e32 v188, 1.0, v188
	v_add_f32_e32 v189, 1.0, v189
	v_add_f32_e32 v190, 1.0, v190
	v_add_f32_e32 v191, 1.0, v191
	v_add_f32_e32 v192, 1.0, v192
	v_add_f32_e32 v193, 1.0, v193
	v_rcp_f32_e32 v186, v186
	v_rcp_f32_e32 v187, v187
	v_rcp_f32_e32 v188, v188
	v_rcp_f32_e32 v189, v189
	v_rcp_f32_e32 v190, v190
	v_rcp_f32_e32 v191, v191
	v_rcp_f32_e32 v192, v192
	v_rcp_f32_e32 v193, v193
	v_pk_mul_f32 v[186:187], v[124:125], v[186:187]
	v_pk_mul_f32 v[188:189], v[126:127], v[188:189]
	v_pk_mul_f32 v[190:191], v[120:121], v[190:191]
	v_pk_mul_f32 v[192:193], v[122:123], v[192:193]
	v_cvt_pk_bf16_f32 v194, v186, v187
	v_cvt_pk_bf16_f32 v195, v188, v189
	v_cvt_pk_bf16_f32 v196, v190, v191
	v_cvt_pk_bf16_f32 v197, v192, v193
	v_mul_f32_e32 v186, 0xbfb8aa3b, v116
	v_mul_f32_e32 v187, 0xbfb8aa3b, v117
	v_mul_f32_e32 v188, 0xbfb8aa3b, v118
	v_mul_f32_e32 v189, 0xbfb8aa3b, v119
	v_mul_f32_e32 v190, 0xbfb8aa3b, v112
	v_mul_f32_e32 v191, 0xbfb8aa3b, v113
	v_mul_f32_e32 v192, 0xbfb8aa3b, v114
	v_mul_f32_e32 v193, 0xbfb8aa3b, v115
	v_exp_f32_e32 v186, v186
	v_exp_f32_e32 v187, v187
	v_exp_f32_e32 v188, v188
	v_exp_f32_e32 v189, v189
	v_exp_f32_e32 v190, v190
	v_exp_f32_e32 v191, v191
	v_exp_f32_e32 v192, v192
	v_exp_f32_e32 v193, v193
	v_add_f32_e32 v186, 1.0, v186
	v_add_f32_e32 v187, 1.0, v187
	v_add_f32_e32 v188, 1.0, v188
	v_add_f32_e32 v189, 1.0, v189
	v_add_f32_e32 v190, 1.0, v190
	v_add_f32_e32 v191, 1.0, v191
	v_add_f32_e32 v192, 1.0, v192
	v_add_f32_e32 v193, 1.0, v193
	v_rcp_f32_e32 v186, v186
	v_rcp_f32_e32 v187, v187
	v_rcp_f32_e32 v188, v188
	v_rcp_f32_e32 v189, v189
	v_rcp_f32_e32 v190, v190
	v_rcp_f32_e32 v191, v191
	v_rcp_f32_e32 v192, v192
	v_rcp_f32_e32 v193, v193
	v_pk_mul_f32 v[186:187], v[116:117], v[186:187]
	v_pk_mul_f32 v[188:189], v[118:119], v[188:189]
	v_pk_mul_f32 v[190:191], v[112:113], v[190:191]
	v_pk_mul_f32 v[192:193], v[114:115], v[192:193]
	v_cvt_pk_bf16_f32 v198, v186, v187
	v_cvt_pk_bf16_f32 v199, v188, v189
	v_cvt_pk_bf16_f32 v200, v190, v191
	v_cvt_pk_bf16_f32 v201, v192, v193
	s_nop 0
	v_permlane16_swap_b32_e32 v194, v196
	v_permlane16_swap_b32_e32 v195, v197
	v_permlane16_swap_b32_e32 v198, v200
	v_permlane16_swap_b32_e32 v199, v201
	s_nop 0
	global_store_dwordx4 v[158:159], v[194:197], off
	global_store_dwordx4 v[158:159], v[198:201], off offset:256
	v_lshl_add_u64 v[158:159], v[158:159], 0, s[16:17]
	v_mul_f32_e32 v186, 0xbfb8aa3b, v108
	v_mul_f32_e32 v187, 0xbfb8aa3b, v109
	v_mul_f32_e32 v188, 0xbfb8aa3b, v110
	v_mul_f32_e32 v189, 0xbfb8aa3b, v111
	v_mul_f32_e32 v190, 0xbfb8aa3b, v104
	v_mul_f32_e32 v191, 0xbfb8aa3b, v105
	v_mul_f32_e32 v192, 0xbfb8aa3b, v106
	v_mul_f32_e32 v193, 0xbfb8aa3b, v107
	v_exp_f32_e32 v186, v186
	v_exp_f32_e32 v187, v187
	v_exp_f32_e32 v188, v188
	v_exp_f32_e32 v189, v189
	v_exp_f32_e32 v190, v190
	v_exp_f32_e32 v191, v191
	v_exp_f32_e32 v192, v192
	v_exp_f32_e32 v193, v193
	v_add_f32_e32 v186, 1.0, v186
	v_add_f32_e32 v187, 1.0, v187
	v_add_f32_e32 v188, 1.0, v188
	v_add_f32_e32 v189, 1.0, v189
	v_add_f32_e32 v190, 1.0, v190
	v_add_f32_e32 v191, 1.0, v191
	v_add_f32_e32 v192, 1.0, v192
	v_add_f32_e32 v193, 1.0, v193
	v_rcp_f32_e32 v186, v186
	v_rcp_f32_e32 v187, v187
	v_rcp_f32_e32 v188, v188
	v_rcp_f32_e32 v189, v189
	v_rcp_f32_e32 v190, v190
	v_rcp_f32_e32 v191, v191
	v_rcp_f32_e32 v192, v192
	v_rcp_f32_e32 v193, v193
	v_pk_mul_f32 v[186:187], v[108:109], v[186:187]
	v_pk_mul_f32 v[188:189], v[110:111], v[188:189]
	v_pk_mul_f32 v[190:191], v[104:105], v[190:191]
	v_pk_mul_f32 v[192:193], v[106:107], v[192:193]
	v_cvt_pk_bf16_f32 v202, v186, v187
	v_cvt_pk_bf16_f32 v203, v188, v189
	v_cvt_pk_bf16_f32 v204, v190, v191
	v_cvt_pk_bf16_f32 v205, v192, v193
	v_mul_f32_e32 v186, 0xbfb8aa3b, v100
	v_mul_f32_e32 v187, 0xbfb8aa3b, v101
	v_mul_f32_e32 v188, 0xbfb8aa3b, v102
	v_mul_f32_e32 v189, 0xbfb8aa3b, v103
	v_mul_f32_e32 v190, 0xbfb8aa3b, v96
	v_mul_f32_e32 v191, 0xbfb8aa3b, v97
	v_mul_f32_e32 v192, 0xbfb8aa3b, v98
	v_mul_f32_e32 v193, 0xbfb8aa3b, v99
	v_exp_f32_e32 v186, v186
	v_exp_f32_e32 v187, v187
	v_exp_f32_e32 v188, v188
	v_exp_f32_e32 v189, v189
	v_exp_f32_e32 v190, v190
	v_exp_f32_e32 v191, v191
	v_exp_f32_e32 v192, v192
	v_exp_f32_e32 v193, v193
	v_add_f32_e32 v186, 1.0, v186
	v_add_f32_e32 v187, 1.0, v187
	v_add_f32_e32 v188, 1.0, v188
	v_add_f32_e32 v189, 1.0, v189
	v_add_f32_e32 v190, 1.0, v190
	v_add_f32_e32 v191, 1.0, v191
	v_add_f32_e32 v192, 1.0, v192
	v_add_f32_e32 v193, 1.0, v193
	v_rcp_f32_e32 v186, v186
	v_rcp_f32_e32 v187, v187
	v_rcp_f32_e32 v188, v188
	v_rcp_f32_e32 v189, v189
	v_rcp_f32_e32 v190, v190
	v_rcp_f32_e32 v191, v191
	v_rcp_f32_e32 v192, v192
	v_rcp_f32_e32 v193, v193
	v_pk_mul_f32 v[186:187], v[100:101], v[186:187]
	v_pk_mul_f32 v[188:189], v[102:103], v[188:189]
	v_pk_mul_f32 v[190:191], v[96:97], v[190:191]
	v_pk_mul_f32 v[192:193], v[98:99], v[192:193]
	v_cvt_pk_bf16_f32 v206, v186, v187
	v_cvt_pk_bf16_f32 v207, v188, v189
	v_cvt_pk_bf16_f32 v208, v190, v191
	v_cvt_pk_bf16_f32 v209, v192, v193
	s_nop 0
	v_permlane16_swap_b32_e32 v202, v204
	v_permlane16_swap_b32_e32 v203, v205
	v_permlane16_swap_b32_e32 v206, v208
	v_permlane16_swap_b32_e32 v207, v209
	s_nop 0
	global_store_dwordx4 v[158:159], v[202:205], off
	global_store_dwordx4 v[158:159], v[206:209], off offset:256
	v_lshl_add_u64 v[158:159], v[158:159], 0, s[16:17]
	v_mul_f32_e32 v186, 0xbfb8aa3b, v92
	v_mul_f32_e32 v187, 0xbfb8aa3b, v93
	v_mul_f32_e32 v188, 0xbfb8aa3b, v94
	v_mul_f32_e32 v189, 0xbfb8aa3b, v95
	v_mul_f32_e32 v190, 0xbfb8aa3b, v88
	v_mul_f32_e32 v191, 0xbfb8aa3b, v89
	v_mul_f32_e32 v192, 0xbfb8aa3b, v90
	v_mul_f32_e32 v193, 0xbfb8aa3b, v91
	v_exp_f32_e32 v186, v186
	v_exp_f32_e32 v187, v187
	v_exp_f32_e32 v188, v188
	v_exp_f32_e32 v189, v189
	v_exp_f32_e32 v190, v190
	v_exp_f32_e32 v191, v191
	v_exp_f32_e32 v192, v192
	v_exp_f32_e32 v193, v193
	v_add_f32_e32 v186, 1.0, v186
	v_add_f32_e32 v187, 1.0, v187
	v_add_f32_e32 v188, 1.0, v188
	v_add_f32_e32 v189, 1.0, v189
	v_add_f32_e32 v190, 1.0, v190
	v_add_f32_e32 v191, 1.0, v191
	v_add_f32_e32 v192, 1.0, v192
	v_add_f32_e32 v193, 1.0, v193
	v_rcp_f32_e32 v186, v186
	v_rcp_f32_e32 v187, v187
	v_rcp_f32_e32 v188, v188
	v_rcp_f32_e32 v189, v189
	v_rcp_f32_e32 v190, v190
	v_rcp_f32_e32 v191, v191
	v_rcp_f32_e32 v192, v192
	v_rcp_f32_e32 v193, v193
	v_pk_mul_f32 v[186:187], v[92:93], v[186:187]
	v_pk_mul_f32 v[188:189], v[94:95], v[188:189]
	v_pk_mul_f32 v[190:191], v[88:89], v[190:191]
	v_pk_mul_f32 v[192:193], v[90:91], v[192:193]
	v_cvt_pk_bf16_f32 v194, v186, v187
	v_cvt_pk_bf16_f32 v195, v188, v189
	v_cvt_pk_bf16_f32 v196, v190, v191
	v_cvt_pk_bf16_f32 v197, v192, v193
	v_mul_f32_e32 v186, 0xbfb8aa3b, v84
	v_mul_f32_e32 v187, 0xbfb8aa3b, v85
	v_mul_f32_e32 v188, 0xbfb8aa3b, v86
	v_mul_f32_e32 v189, 0xbfb8aa3b, v87
	v_mul_f32_e32 v190, 0xbfb8aa3b, v80
	v_mul_f32_e32 v191, 0xbfb8aa3b, v81
	v_mul_f32_e32 v192, 0xbfb8aa3b, v82
	v_mul_f32_e32 v193, 0xbfb8aa3b, v83
	v_exp_f32_e32 v186, v186
	v_exp_f32_e32 v187, v187
	v_exp_f32_e32 v188, v188
	v_exp_f32_e32 v189, v189
	v_exp_f32_e32 v190, v190
	v_exp_f32_e32 v191, v191
	v_exp_f32_e32 v192, v192
	v_exp_f32_e32 v193, v193
	v_add_f32_e32 v186, 1.0, v186
	v_add_f32_e32 v187, 1.0, v187
	v_add_f32_e32 v188, 1.0, v188
	v_add_f32_e32 v189, 1.0, v189
	v_add_f32_e32 v190, 1.0, v190
	v_add_f32_e32 v191, 1.0, v191
	v_add_f32_e32 v192, 1.0, v192
	v_add_f32_e32 v193, 1.0, v193
	v_rcp_f32_e32 v186, v186
	v_rcp_f32_e32 v187, v187
	v_rcp_f32_e32 v188, v188
	v_rcp_f32_e32 v189, v189
	v_rcp_f32_e32 v190, v190
	v_rcp_f32_e32 v191, v191
	v_rcp_f32_e32 v192, v192
	v_rcp_f32_e32 v193, v193
	v_pk_mul_f32 v[186:187], v[84:85], v[186:187]
	v_pk_mul_f32 v[188:189], v[86:87], v[188:189]
	v_pk_mul_f32 v[190:191], v[80:81], v[190:191]
	v_pk_mul_f32 v[192:193], v[82:83], v[192:193]
	v_cvt_pk_bf16_f32 v198, v186, v187
	v_cvt_pk_bf16_f32 v199, v188, v189
	v_cvt_pk_bf16_f32 v200, v190, v191
	v_cvt_pk_bf16_f32 v201, v192, v193
	s_nop 0
	v_permlane16_swap_b32_e32 v194, v196
	v_permlane16_swap_b32_e32 v195, v197
	v_permlane16_swap_b32_e32 v198, v200
	v_permlane16_swap_b32_e32 v199, v201
	s_nop 0
	global_store_dwordx4 v[158:159], v[194:197], off
	global_store_dwordx4 v[158:159], v[198:201], off offset:256
	v_lshl_add_u64 v[158:159], v[158:159], 0, s[16:17]
	v_mul_f32_e32 v186, 0xbfb8aa3b, v76
	v_mul_f32_e32 v187, 0xbfb8aa3b, v77
	v_mul_f32_e32 v188, 0xbfb8aa3b, v78
	v_mul_f32_e32 v189, 0xbfb8aa3b, v79
	v_mul_f32_e32 v190, 0xbfb8aa3b, v72
	v_mul_f32_e32 v191, 0xbfb8aa3b, v73
	v_mul_f32_e32 v192, 0xbfb8aa3b, v74
	v_mul_f32_e32 v193, 0xbfb8aa3b, v75
	v_exp_f32_e32 v186, v186
	v_exp_f32_e32 v187, v187
	v_exp_f32_e32 v188, v188
	v_exp_f32_e32 v189, v189
	v_exp_f32_e32 v190, v190
	v_exp_f32_e32 v191, v191
	v_exp_f32_e32 v192, v192
	v_exp_f32_e32 v193, v193
	v_add_f32_e32 v186, 1.0, v186
	v_add_f32_e32 v187, 1.0, v187
	v_add_f32_e32 v188, 1.0, v188
	v_add_f32_e32 v189, 1.0, v189
	v_add_f32_e32 v190, 1.0, v190
	v_add_f32_e32 v191, 1.0, v191
	v_add_f32_e32 v192, 1.0, v192
	v_add_f32_e32 v193, 1.0, v193
	v_rcp_f32_e32 v186, v186
	v_rcp_f32_e32 v187, v187
	v_rcp_f32_e32 v188, v188
	v_rcp_f32_e32 v189, v189
	v_rcp_f32_e32 v190, v190
	v_rcp_f32_e32 v191, v191
	v_rcp_f32_e32 v192, v192
	v_rcp_f32_e32 v193, v193
	v_pk_mul_f32 v[186:187], v[76:77], v[186:187]
	v_pk_mul_f32 v[188:189], v[78:79], v[188:189]
	v_pk_mul_f32 v[190:191], v[72:73], v[190:191]
	v_pk_mul_f32 v[192:193], v[74:75], v[192:193]
	v_cvt_pk_bf16_f32 v202, v186, v187
	v_cvt_pk_bf16_f32 v203, v188, v189
	v_cvt_pk_bf16_f32 v204, v190, v191
	v_cvt_pk_bf16_f32 v205, v192, v193
	v_mul_f32_e32 v186, 0xbfb8aa3b, v68
	v_mul_f32_e32 v187, 0xbfb8aa3b, v69
	v_mul_f32_e32 v188, 0xbfb8aa3b, v70
	v_mul_f32_e32 v189, 0xbfb8aa3b, v71
	v_mul_f32_e32 v190, 0xbfb8aa3b, v64
	v_mul_f32_e32 v191, 0xbfb8aa3b, v65
	v_mul_f32_e32 v192, 0xbfb8aa3b, v66
	v_mul_f32_e32 v193, 0xbfb8aa3b, v67
	v_exp_f32_e32 v186, v186
	v_exp_f32_e32 v187, v187
	v_exp_f32_e32 v188, v188
	v_exp_f32_e32 v189, v189
	v_exp_f32_e32 v190, v190
	v_exp_f32_e32 v191, v191
	v_exp_f32_e32 v192, v192
	v_exp_f32_e32 v193, v193
	v_add_f32_e32 v186, 1.0, v186
	v_add_f32_e32 v187, 1.0, v187
	v_add_f32_e32 v188, 1.0, v188
	v_add_f32_e32 v189, 1.0, v189
	v_add_f32_e32 v190, 1.0, v190
	v_add_f32_e32 v191, 1.0, v191
	v_add_f32_e32 v192, 1.0, v192
	v_add_f32_e32 v193, 1.0, v193
	v_rcp_f32_e32 v186, v186
	v_rcp_f32_e32 v187, v187
	v_rcp_f32_e32 v188, v188
	v_rcp_f32_e32 v189, v189
	v_rcp_f32_e32 v190, v190
	v_rcp_f32_e32 v191, v191
	v_rcp_f32_e32 v192, v192
	v_rcp_f32_e32 v193, v193
	v_pk_mul_f32 v[186:187], v[68:69], v[186:187]
	v_pk_mul_f32 v[188:189], v[70:71], v[188:189]
	v_pk_mul_f32 v[190:191], v[64:65], v[190:191]
	v_pk_mul_f32 v[192:193], v[66:67], v[192:193]
	v_cvt_pk_bf16_f32 v206, v186, v187
	v_cvt_pk_bf16_f32 v207, v188, v189
	v_cvt_pk_bf16_f32 v208, v190, v191
	v_cvt_pk_bf16_f32 v209, v192, v193
	s_nop 0
	v_permlane16_swap_b32_e32 v202, v204
	v_permlane16_swap_b32_e32 v203, v205
	v_permlane16_swap_b32_e32 v206, v208
	v_permlane16_swap_b32_e32 v207, v209
	s_nop 0
	global_store_dwordx4 v[158:159], v[202:205], off
	global_store_dwordx4 v[158:159], v[206:209], off offset:256
	v_lshl_add_u64 v[158:159], v[158:159], 0, s[18:19]
	v_mul_f32_e32 v186, 0xbfb8aa3b, v60
	v_mul_f32_e32 v187, 0xbfb8aa3b, v61
	v_mul_f32_e32 v188, 0xbfb8aa3b, v62
	v_mul_f32_e32 v189, 0xbfb8aa3b, v63
	v_mul_f32_e32 v190, 0xbfb8aa3b, v56
	v_mul_f32_e32 v191, 0xbfb8aa3b, v57
	v_mul_f32_e32 v192, 0xbfb8aa3b, v58
	v_mul_f32_e32 v193, 0xbfb8aa3b, v59
	v_exp_f32_e32 v186, v186
	v_exp_f32_e32 v187, v187
	v_exp_f32_e32 v188, v188
	v_exp_f32_e32 v189, v189
	v_exp_f32_e32 v190, v190
	v_exp_f32_e32 v191, v191
	v_exp_f32_e32 v192, v192
	v_exp_f32_e32 v193, v193
	v_add_f32_e32 v186, 1.0, v186
	v_add_f32_e32 v187, 1.0, v187
	v_add_f32_e32 v188, 1.0, v188
	v_add_f32_e32 v189, 1.0, v189
	v_add_f32_e32 v190, 1.0, v190
	v_add_f32_e32 v191, 1.0, v191
	v_add_f32_e32 v192, 1.0, v192
	v_add_f32_e32 v193, 1.0, v193
	v_rcp_f32_e32 v186, v186
	v_rcp_f32_e32 v187, v187
	v_rcp_f32_e32 v188, v188
	v_rcp_f32_e32 v189, v189
	v_rcp_f32_e32 v190, v190
	v_rcp_f32_e32 v191, v191
	v_rcp_f32_e32 v192, v192
	v_rcp_f32_e32 v193, v193
	v_pk_mul_f32 v[186:187], v[60:61], v[186:187]
	v_pk_mul_f32 v[188:189], v[62:63], v[188:189]
	v_pk_mul_f32 v[190:191], v[56:57], v[190:191]
	v_pk_mul_f32 v[192:193], v[58:59], v[192:193]
	v_cvt_pk_bf16_f32 v194, v186, v187
	v_cvt_pk_bf16_f32 v195, v188, v189
	v_cvt_pk_bf16_f32 v196, v190, v191
	v_cvt_pk_bf16_f32 v197, v192, v193
	v_mul_f32_e32 v186, 0xbfb8aa3b, v52
	v_mul_f32_e32 v187, 0xbfb8aa3b, v53
	v_mul_f32_e32 v188, 0xbfb8aa3b, v54
	v_mul_f32_e32 v189, 0xbfb8aa3b, v55
	v_mul_f32_e32 v190, 0xbfb8aa3b, v48
	v_mul_f32_e32 v191, 0xbfb8aa3b, v49
	v_mul_f32_e32 v192, 0xbfb8aa3b, v50
	v_mul_f32_e32 v193, 0xbfb8aa3b, v51
	v_exp_f32_e32 v186, v186
	v_exp_f32_e32 v187, v187
	v_exp_f32_e32 v188, v188
	v_exp_f32_e32 v189, v189
	v_exp_f32_e32 v190, v190
	v_exp_f32_e32 v191, v191
	v_exp_f32_e32 v192, v192
	v_exp_f32_e32 v193, v193
	v_add_f32_e32 v186, 1.0, v186
	v_add_f32_e32 v187, 1.0, v187
	v_add_f32_e32 v188, 1.0, v188
	v_add_f32_e32 v189, 1.0, v189
	v_add_f32_e32 v190, 1.0, v190
	v_add_f32_e32 v191, 1.0, v191
	v_add_f32_e32 v192, 1.0, v192
	v_add_f32_e32 v193, 1.0, v193
	v_rcp_f32_e32 v186, v186
	v_rcp_f32_e32 v187, v187
	v_rcp_f32_e32 v188, v188
	v_rcp_f32_e32 v189, v189
	v_rcp_f32_e32 v190, v190
	v_rcp_f32_e32 v191, v191
	v_rcp_f32_e32 v192, v192
	v_rcp_f32_e32 v193, v193
	v_pk_mul_f32 v[186:187], v[52:53], v[186:187]
	v_pk_mul_f32 v[188:189], v[54:55], v[188:189]
	v_pk_mul_f32 v[190:191], v[48:49], v[190:191]
	v_pk_mul_f32 v[192:193], v[50:51], v[192:193]
	v_cvt_pk_bf16_f32 v198, v186, v187
	v_cvt_pk_bf16_f32 v199, v188, v189
	v_cvt_pk_bf16_f32 v200, v190, v191
	v_cvt_pk_bf16_f32 v201, v192, v193
	s_nop 0
	v_permlane16_swap_b32_e32 v194, v196
	v_permlane16_swap_b32_e32 v195, v197
	v_permlane16_swap_b32_e32 v198, v200
	v_permlane16_swap_b32_e32 v199, v201
	s_nop 0
	global_store_dwordx4 v[158:159], v[194:197], off
	global_store_dwordx4 v[158:159], v[198:201], off offset:256
	v_lshl_add_u64 v[158:159], v[158:159], 0, s[16:17]
	v_mul_f32_e32 v186, 0xbfb8aa3b, v44
	v_mul_f32_e32 v187, 0xbfb8aa3b, v45
	v_mul_f32_e32 v188, 0xbfb8aa3b, v46
	v_mul_f32_e32 v189, 0xbfb8aa3b, v47
	v_mul_f32_e32 v190, 0xbfb8aa3b, v40
	v_mul_f32_e32 v191, 0xbfb8aa3b, v41
	v_mul_f32_e32 v192, 0xbfb8aa3b, v42
	v_mul_f32_e32 v193, 0xbfb8aa3b, v43
	v_exp_f32_e32 v186, v186
	v_exp_f32_e32 v187, v187
	v_exp_f32_e32 v188, v188
	v_exp_f32_e32 v189, v189
	v_exp_f32_e32 v190, v190
	v_exp_f32_e32 v191, v191
	v_exp_f32_e32 v192, v192
	v_exp_f32_e32 v193, v193
	v_add_f32_e32 v186, 1.0, v186
	v_add_f32_e32 v187, 1.0, v187
	v_add_f32_e32 v188, 1.0, v188
	v_add_f32_e32 v189, 1.0, v189
	v_add_f32_e32 v190, 1.0, v190
	v_add_f32_e32 v191, 1.0, v191
	v_add_f32_e32 v192, 1.0, v192
	v_add_f32_e32 v193, 1.0, v193
	v_rcp_f32_e32 v186, v186
	v_rcp_f32_e32 v187, v187
	v_rcp_f32_e32 v188, v188
	v_rcp_f32_e32 v189, v189
	v_rcp_f32_e32 v190, v190
	v_rcp_f32_e32 v191, v191
	v_rcp_f32_e32 v192, v192
	v_rcp_f32_e32 v193, v193
	v_pk_mul_f32 v[186:187], v[44:45], v[186:187]
	v_pk_mul_f32 v[188:189], v[46:47], v[188:189]
	v_pk_mul_f32 v[190:191], v[40:41], v[190:191]
	v_pk_mul_f32 v[192:193], v[42:43], v[192:193]
	v_cvt_pk_bf16_f32 v202, v186, v187
	v_cvt_pk_bf16_f32 v203, v188, v189
	v_cvt_pk_bf16_f32 v204, v190, v191
	v_cvt_pk_bf16_f32 v205, v192, v193
	v_mul_f32_e32 v186, 0xbfb8aa3b, v36
	v_mul_f32_e32 v187, 0xbfb8aa3b, v37
	v_mul_f32_e32 v188, 0xbfb8aa3b, v38
	v_mul_f32_e32 v189, 0xbfb8aa3b, v39
	v_mul_f32_e32 v190, 0xbfb8aa3b, v32
	v_mul_f32_e32 v191, 0xbfb8aa3b, v33
	v_mul_f32_e32 v192, 0xbfb8aa3b, v34
	v_mul_f32_e32 v193, 0xbfb8aa3b, v35
	v_exp_f32_e32 v186, v186
	v_exp_f32_e32 v187, v187
	v_exp_f32_e32 v188, v188
	v_exp_f32_e32 v189, v189
	v_exp_f32_e32 v190, v190
	v_exp_f32_e32 v191, v191
	v_exp_f32_e32 v192, v192
	v_exp_f32_e32 v193, v193
	v_add_f32_e32 v186, 1.0, v186
	v_add_f32_e32 v187, 1.0, v187
	v_add_f32_e32 v188, 1.0, v188
	v_add_f32_e32 v189, 1.0, v189
	v_add_f32_e32 v190, 1.0, v190
	v_add_f32_e32 v191, 1.0, v191
	v_add_f32_e32 v192, 1.0, v192
	v_add_f32_e32 v193, 1.0, v193
	v_rcp_f32_e32 v186, v186
	v_rcp_f32_e32 v187, v187
	v_rcp_f32_e32 v188, v188
	v_rcp_f32_e32 v189, v189
	v_rcp_f32_e32 v190, v190
	v_rcp_f32_e32 v191, v191
	v_rcp_f32_e32 v192, v192
	v_rcp_f32_e32 v193, v193
	v_pk_mul_f32 v[186:187], v[36:37], v[186:187]
	v_pk_mul_f32 v[188:189], v[38:39], v[188:189]
	v_pk_mul_f32 v[190:191], v[32:33], v[190:191]
	v_pk_mul_f32 v[192:193], v[34:35], v[192:193]
	v_cvt_pk_bf16_f32 v206, v186, v187
	v_cvt_pk_bf16_f32 v207, v188, v189
	v_cvt_pk_bf16_f32 v208, v190, v191
	v_cvt_pk_bf16_f32 v209, v192, v193
	s_nop 0
	v_permlane16_swap_b32_e32 v202, v204
	v_permlane16_swap_b32_e32 v203, v205
	v_permlane16_swap_b32_e32 v206, v208
	v_permlane16_swap_b32_e32 v207, v209
	s_nop 0
	global_store_dwordx4 v[158:159], v[202:205], off
	global_store_dwordx4 v[158:159], v[206:209], off offset:256
	v_lshl_add_u64 v[158:159], v[158:159], 0, s[16:17]
	v_mul_f32_e32 v186, 0xbfb8aa3b, v28
	v_mul_f32_e32 v187, 0xbfb8aa3b, v29
	v_mul_f32_e32 v188, 0xbfb8aa3b, v30
	v_mul_f32_e32 v189, 0xbfb8aa3b, v31
	v_mul_f32_e32 v190, 0xbfb8aa3b, v24
	v_mul_f32_e32 v191, 0xbfb8aa3b, v25
	v_mul_f32_e32 v192, 0xbfb8aa3b, v26
	v_mul_f32_e32 v193, 0xbfb8aa3b, v27
	v_exp_f32_e32 v186, v186
	v_exp_f32_e32 v187, v187
	v_exp_f32_e32 v188, v188
	v_exp_f32_e32 v189, v189
	v_exp_f32_e32 v190, v190
	v_exp_f32_e32 v191, v191
	v_exp_f32_e32 v192, v192
	v_exp_f32_e32 v193, v193
	v_add_f32_e32 v186, 1.0, v186
	v_add_f32_e32 v187, 1.0, v187
	v_add_f32_e32 v188, 1.0, v188
	v_add_f32_e32 v189, 1.0, v189
	v_add_f32_e32 v190, 1.0, v190
	v_add_f32_e32 v191, 1.0, v191
	v_add_f32_e32 v192, 1.0, v192
	v_add_f32_e32 v193, 1.0, v193
	v_rcp_f32_e32 v186, v186
	v_rcp_f32_e32 v187, v187
	v_rcp_f32_e32 v188, v188
	v_rcp_f32_e32 v189, v189
	v_rcp_f32_e32 v190, v190
	v_rcp_f32_e32 v191, v191
	v_rcp_f32_e32 v192, v192
	v_rcp_f32_e32 v193, v193
	v_pk_mul_f32 v[186:187], v[28:29], v[186:187]
	v_pk_mul_f32 v[188:189], v[30:31], v[188:189]
	v_pk_mul_f32 v[190:191], v[24:25], v[190:191]
	v_pk_mul_f32 v[192:193], v[26:27], v[192:193]
	v_cvt_pk_bf16_f32 v194, v186, v187
	v_cvt_pk_bf16_f32 v195, v188, v189
	v_cvt_pk_bf16_f32 v196, v190, v191
	v_cvt_pk_bf16_f32 v197, v192, v193
	v_mul_f32_e32 v186, 0xbfb8aa3b, v20
	v_mul_f32_e32 v187, 0xbfb8aa3b, v21
	v_mul_f32_e32 v188, 0xbfb8aa3b, v22
	v_mul_f32_e32 v189, 0xbfb8aa3b, v23
	v_mul_f32_e32 v190, 0xbfb8aa3b, v16
	v_mul_f32_e32 v191, 0xbfb8aa3b, v17
	v_mul_f32_e32 v192, 0xbfb8aa3b, v18
	v_mul_f32_e32 v193, 0xbfb8aa3b, v19
	v_exp_f32_e32 v186, v186
	v_exp_f32_e32 v187, v187
	v_exp_f32_e32 v188, v188
	v_exp_f32_e32 v189, v189
	v_exp_f32_e32 v190, v190
	v_exp_f32_e32 v191, v191
	v_exp_f32_e32 v192, v192
	v_exp_f32_e32 v193, v193
	v_add_f32_e32 v186, 1.0, v186
	v_add_f32_e32 v187, 1.0, v187
	v_add_f32_e32 v188, 1.0, v188
	v_add_f32_e32 v189, 1.0, v189
	v_add_f32_e32 v190, 1.0, v190
	v_add_f32_e32 v191, 1.0, v191
	v_add_f32_e32 v192, 1.0, v192
	v_add_f32_e32 v193, 1.0, v193
	v_rcp_f32_e32 v186, v186
	v_rcp_f32_e32 v187, v187
	v_rcp_f32_e32 v188, v188
	v_rcp_f32_e32 v189, v189
	v_rcp_f32_e32 v190, v190
	v_rcp_f32_e32 v191, v191
	v_rcp_f32_e32 v192, v192
	v_rcp_f32_e32 v193, v193
	v_pk_mul_f32 v[186:187], v[20:21], v[186:187]
	v_pk_mul_f32 v[188:189], v[22:23], v[188:189]
	v_pk_mul_f32 v[190:191], v[16:17], v[190:191]
	v_pk_mul_f32 v[192:193], v[18:19], v[192:193]
	v_cvt_pk_bf16_f32 v198, v186, v187
	v_cvt_pk_bf16_f32 v199, v188, v189
	v_cvt_pk_bf16_f32 v200, v190, v191
	v_cvt_pk_bf16_f32 v201, v192, v193
	s_nop 0
	v_permlane16_swap_b32_e32 v194, v196
	v_permlane16_swap_b32_e32 v195, v197
	v_permlane16_swap_b32_e32 v198, v200
	v_permlane16_swap_b32_e32 v199, v201
	s_nop 0
	global_store_dwordx4 v[158:159], v[194:197], off
	global_store_dwordx4 v[158:159], v[198:201], off offset:256
	v_lshl_add_u64 v[158:159], v[158:159], 0, s[16:17]
	v_mul_f32_e32 v186, 0xbfb8aa3b, v12
	v_mul_f32_e32 v187, 0xbfb8aa3b, v13
	v_mul_f32_e32 v188, 0xbfb8aa3b, v14
	v_mul_f32_e32 v189, 0xbfb8aa3b, v15
	v_mul_f32_e32 v190, 0xbfb8aa3b, v8
	v_mul_f32_e32 v191, 0xbfb8aa3b, v9
	v_mul_f32_e32 v192, 0xbfb8aa3b, v10
	v_mul_f32_e32 v193, 0xbfb8aa3b, v11
	v_exp_f32_e32 v186, v186
	v_exp_f32_e32 v187, v187
	v_exp_f32_e32 v188, v188
	v_exp_f32_e32 v189, v189
	v_exp_f32_e32 v190, v190
	v_exp_f32_e32 v191, v191
	v_exp_f32_e32 v192, v192
	v_exp_f32_e32 v193, v193
	v_add_f32_e32 v186, 1.0, v186
	v_add_f32_e32 v187, 1.0, v187
	v_add_f32_e32 v188, 1.0, v188
	v_add_f32_e32 v189, 1.0, v189
	v_add_f32_e32 v190, 1.0, v190
	v_add_f32_e32 v191, 1.0, v191
	v_add_f32_e32 v192, 1.0, v192
	v_add_f32_e32 v193, 1.0, v193
	v_rcp_f32_e32 v186, v186
	v_rcp_f32_e32 v187, v187
	v_rcp_f32_e32 v188, v188
	v_rcp_f32_e32 v189, v189
	v_rcp_f32_e32 v190, v190
	v_rcp_f32_e32 v191, v191
	v_rcp_f32_e32 v192, v192
	v_rcp_f32_e32 v193, v193
	v_pk_mul_f32 v[186:187], v[12:13], v[186:187]
	v_pk_mul_f32 v[188:189], v[14:15], v[188:189]
	v_pk_mul_f32 v[190:191], v[8:9], v[190:191]
	v_pk_mul_f32 v[192:193], v[10:11], v[192:193]
	v_cvt_pk_bf16_f32 v202, v186, v187
	v_cvt_pk_bf16_f32 v203, v188, v189
	v_cvt_pk_bf16_f32 v204, v190, v191
	v_cvt_pk_bf16_f32 v205, v192, v193
	v_mul_f32_e32 v186, 0xbfb8aa3b, v4
	v_mul_f32_e32 v187, 0xbfb8aa3b, v5
	v_mul_f32_e32 v188, 0xbfb8aa3b, v6
	v_mul_f32_e32 v189, 0xbfb8aa3b, v7
	v_mul_f32_e32 v190, 0xbfb8aa3b, v0
	v_mul_f32_e32 v191, 0xbfb8aa3b, v1
	v_mul_f32_e32 v192, 0xbfb8aa3b, v2
	v_mul_f32_e32 v193, 0xbfb8aa3b, v3
	v_exp_f32_e32 v186, v186
	v_exp_f32_e32 v187, v187
	v_exp_f32_e32 v188, v188
	v_exp_f32_e32 v189, v189
	v_exp_f32_e32 v190, v190
	v_exp_f32_e32 v191, v191
	v_exp_f32_e32 v192, v192
	v_exp_f32_e32 v193, v193
	v_add_f32_e32 v186, 1.0, v186
	v_add_f32_e32 v187, 1.0, v187
	v_add_f32_e32 v188, 1.0, v188
	v_add_f32_e32 v189, 1.0, v189
	v_add_f32_e32 v190, 1.0, v190
	v_add_f32_e32 v191, 1.0, v191
	v_add_f32_e32 v192, 1.0, v192
	v_add_f32_e32 v193, 1.0, v193
	v_rcp_f32_e32 v186, v186
	v_rcp_f32_e32 v187, v187
	v_rcp_f32_e32 v188, v188
	v_rcp_f32_e32 v189, v189
	v_rcp_f32_e32 v190, v190
	v_rcp_f32_e32 v191, v191
	v_rcp_f32_e32 v192, v192
	v_rcp_f32_e32 v193, v193
	v_pk_mul_f32 v[186:187], v[4:5], v[186:187]
	v_pk_mul_f32 v[188:189], v[6:7], v[188:189]
	v_pk_mul_f32 v[190:191], v[0:1], v[190:191]
	v_pk_mul_f32 v[192:193], v[2:3], v[192:193]
	v_cvt_pk_bf16_f32 v206, v186, v187
	v_cvt_pk_bf16_f32 v207, v188, v189
	v_cvt_pk_bf16_f32 v208, v190, v191
	v_cvt_pk_bf16_f32 v209, v192, v193
	s_nop 0
	v_permlane16_swap_b32_e32 v202, v204
	v_permlane16_swap_b32_e32 v203, v205
	v_permlane16_swap_b32_e32 v206, v208
	v_permlane16_swap_b32_e32 v207, v209
	s_nop 0
	global_store_dwordx4 v[158:159], v[202:205], off
	global_store_dwordx4 v[158:159], v[206:209], off offset:256
	s_branch .LBB0_224
.Lepi_hg_forget:
	s_and_b32 s4, s2, 3
	s_lshl_b32 s4, s4, 8
	v_or_b32_e32 v160, s4, v166
	v_lshlrev_b32_e32 v160, 2, v160
	global_load_dwordx4 v[210:213], v160, s[98:99]
	global_load_dwordx4 v[214:217], v160, s[98:99] offset:64
	global_load_dwordx4 v[218:221], v160, s[98:99] offset:512
	global_load_dwordx4 v[222:225], v160, s[98:99] offset:576
	s_waitcnt vmcnt(0)
	v_mul_f32_e32 v186, 0x3fb8aa3b, v124
	v_mul_f32_e32 v187, 0x3fb8aa3b, v125
	v_mul_f32_e32 v188, 0x3fb8aa3b, v126
	v_mul_f32_e32 v189, 0x3fb8aa3b, v127
	v_mul_f32_e32 v190, 0x3fb8aa3b, v120
	v_mul_f32_e32 v191, 0x3fb8aa3b, v121
	v_mul_f32_e32 v192, 0x3fb8aa3b, v122
	v_mul_f32_e32 v193, 0x3fb8aa3b, v123
	v_exp_f32_e32 v186, v186
	v_exp_f32_e32 v187, v187
	v_exp_f32_e32 v188, v188
	v_exp_f32_e32 v189, v189
	v_exp_f32_e32 v190, v190
	v_exp_f32_e32 v191, v191
	v_exp_f32_e32 v192, v192
	v_exp_f32_e32 v193, v193
	v_add_f32_e32 v186, 1.0, v186
	v_add_f32_e32 v187, 1.0, v187
	v_add_f32_e32 v188, 1.0, v188
	v_add_f32_e32 v189, 1.0, v189
	v_add_f32_e32 v190, 1.0, v190
	v_add_f32_e32 v191, 1.0, v191
	v_add_f32_e32 v192, 1.0, v192
	v_add_f32_e32 v193, 1.0, v193
	v_rcp_f32_e32 v186, v186
	v_rcp_f32_e32 v187, v187
	v_rcp_f32_e32 v188, v188
	v_rcp_f32_e32 v189, v189
	v_rcp_f32_e32 v190, v190
	v_rcp_f32_e32 v191, v191
	v_rcp_f32_e32 v192, v192
	v_rcp_f32_e32 v193, v193
	v_pk_mul_f32 v[186:187], v[186:187], v[210:211]
	v_pk_mul_f32 v[188:189], v[188:189], v[212:213]
	v_pk_mul_f32 v[190:191], v[190:191], v[214:215]
	v_pk_mul_f32 v[192:193], v[192:193], v[216:217]
	v_cvt_pk_bf16_f32 v194, v186, v187
	v_cvt_pk_bf16_f32 v195, v188, v189
	v_cvt_pk_bf16_f32 v196, v190, v191
	v_cvt_pk_bf16_f32 v197, v192, v193
	v_mul_f32_e32 v186, 0x3fb8aa3b, v116
	v_mul_f32_e32 v187, 0x3fb8aa3b, v117
	v_mul_f32_e32 v188, 0x3fb8aa3b, v118
	v_mul_f32_e32 v189, 0x3fb8aa3b, v119
	v_mul_f32_e32 v190, 0x3fb8aa3b, v112
	v_mul_f32_e32 v191, 0x3fb8aa3b, v113
	v_mul_f32_e32 v192, 0x3fb8aa3b, v114
	v_mul_f32_e32 v193, 0x3fb8aa3b, v115
	v_exp_f32_e32 v186, v186
	v_exp_f32_e32 v187, v187
	v_exp_f32_e32 v188, v188
	v_exp_f32_e32 v189, v189
	v_exp_f32_e32 v190, v190
	v_exp_f32_e32 v191, v191
	v_exp_f32_e32 v192, v192
	v_exp_f32_e32 v193, v193
	v_add_f32_e32 v186, 1.0, v186
	v_add_f32_e32 v187, 1.0, v187
	v_add_f32_e32 v188, 1.0, v188
	v_add_f32_e32 v189, 1.0, v189
	v_add_f32_e32 v190, 1.0, v190
	v_add_f32_e32 v191, 1.0, v191
	v_add_f32_e32 v192, 1.0, v192
	v_add_f32_e32 v193, 1.0, v193
	v_rcp_f32_e32 v186, v186
	v_rcp_f32_e32 v187, v187
	v_rcp_f32_e32 v188, v188
	v_rcp_f32_e32 v189, v189
	v_rcp_f32_e32 v190, v190
	v_rcp_f32_e32 v191, v191
	v_rcp_f32_e32 v192, v192
	v_rcp_f32_e32 v193, v193
	v_pk_mul_f32 v[186:187], v[186:187], v[218:219]
	v_pk_mul_f32 v[188:189], v[188:189], v[220:221]
	v_pk_mul_f32 v[190:191], v[190:191], v[222:223]
	v_pk_mul_f32 v[192:193], v[192:193], v[224:225]
	v_cvt_pk_bf16_f32 v198, v186, v187
	v_cvt_pk_bf16_f32 v199, v188, v189
	v_cvt_pk_bf16_f32 v200, v190, v191
	v_cvt_pk_bf16_f32 v201, v192, v193
	s_nop 0
	v_permlane16_swap_b32_e32 v194, v196
	v_permlane16_swap_b32_e32 v195, v197
	v_permlane16_swap_b32_e32 v198, v200
	v_permlane16_swap_b32_e32 v199, v201
	s_nop 0
	global_store_dwordx4 v[158:159], v[194:197], off
	global_store_dwordx4 v[158:159], v[198:201], off offset:256
	v_lshl_add_u64 v[158:159], v[158:159], 0, s[16:17]
	v_mul_f32_e32 v186, 0x3fb8aa3b, v108
	v_mul_f32_e32 v187, 0x3fb8aa3b, v109
	v_mul_f32_e32 v188, 0x3fb8aa3b, v110
	v_mul_f32_e32 v189, 0x3fb8aa3b, v111
	v_mul_f32_e32 v190, 0x3fb8aa3b, v104
	v_mul_f32_e32 v191, 0x3fb8aa3b, v105
	v_mul_f32_e32 v192, 0x3fb8aa3b, v106
	v_mul_f32_e32 v193, 0x3fb8aa3b, v107
	v_exp_f32_e32 v186, v186
	v_exp_f32_e32 v187, v187
	v_exp_f32_e32 v188, v188
	v_exp_f32_e32 v189, v189
	v_exp_f32_e32 v190, v190
	v_exp_f32_e32 v191, v191
	v_exp_f32_e32 v192, v192
	v_exp_f32_e32 v193, v193
	v_add_f32_e32 v186, 1.0, v186
	v_add_f32_e32 v187, 1.0, v187
	v_add_f32_e32 v188, 1.0, v188
	v_add_f32_e32 v189, 1.0, v189
	v_add_f32_e32 v190, 1.0, v190
	v_add_f32_e32 v191, 1.0, v191
	v_add_f32_e32 v192, 1.0, v192
	v_add_f32_e32 v193, 1.0, v193
	v_rcp_f32_e32 v186, v186
	v_rcp_f32_e32 v187, v187
	v_rcp_f32_e32 v188, v188
	v_rcp_f32_e32 v189, v189
	v_rcp_f32_e32 v190, v190
	v_rcp_f32_e32 v191, v191
	v_rcp_f32_e32 v192, v192
	v_rcp_f32_e32 v193, v193
	v_pk_mul_f32 v[186:187], v[186:187], v[210:211]
	v_pk_mul_f32 v[188:189], v[188:189], v[212:213]
	v_pk_mul_f32 v[190:191], v[190:191], v[214:215]
	v_pk_mul_f32 v[192:193], v[192:193], v[216:217]
	v_cvt_pk_bf16_f32 v202, v186, v187
	v_cvt_pk_bf16_f32 v203, v188, v189
	v_cvt_pk_bf16_f32 v204, v190, v191
	v_cvt_pk_bf16_f32 v205, v192, v193
	v_mul_f32_e32 v186, 0x3fb8aa3b, v100
	v_mul_f32_e32 v187, 0x3fb8aa3b, v101
	v_mul_f32_e32 v188, 0x3fb8aa3b, v102
	v_mul_f32_e32 v189, 0x3fb8aa3b, v103
	v_mul_f32_e32 v190, 0x3fb8aa3b, v96
	v_mul_f32_e32 v191, 0x3fb8aa3b, v97
	v_mul_f32_e32 v192, 0x3fb8aa3b, v98
	v_mul_f32_e32 v193, 0x3fb8aa3b, v99
	v_exp_f32_e32 v186, v186
	v_exp_f32_e32 v187, v187
	v_exp_f32_e32 v188, v188
	v_exp_f32_e32 v189, v189
	v_exp_f32_e32 v190, v190
	v_exp_f32_e32 v191, v191
	v_exp_f32_e32 v192, v192
	v_exp_f32_e32 v193, v193
	v_add_f32_e32 v186, 1.0, v186
	v_add_f32_e32 v187, 1.0, v187
	v_add_f32_e32 v188, 1.0, v188
	v_add_f32_e32 v189, 1.0, v189
	v_add_f32_e32 v190, 1.0, v190
	v_add_f32_e32 v191, 1.0, v191
	v_add_f32_e32 v192, 1.0, v192
	v_add_f32_e32 v193, 1.0, v193
	v_rcp_f32_e32 v186, v186
	v_rcp_f32_e32 v187, v187
	v_rcp_f32_e32 v188, v188
	v_rcp_f32_e32 v189, v189
	v_rcp_f32_e32 v190, v190
	v_rcp_f32_e32 v191, v191
	v_rcp_f32_e32 v192, v192
	v_rcp_f32_e32 v193, v193
	v_pk_mul_f32 v[186:187], v[186:187], v[218:219]
	v_pk_mul_f32 v[188:189], v[188:189], v[220:221]
	v_pk_mul_f32 v[190:191], v[190:191], v[222:223]
	v_pk_mul_f32 v[192:193], v[192:193], v[224:225]
	v_cvt_pk_bf16_f32 v206, v186, v187
	v_cvt_pk_bf16_f32 v207, v188, v189
	v_cvt_pk_bf16_f32 v208, v190, v191
	v_cvt_pk_bf16_f32 v209, v192, v193
	s_nop 0
	v_permlane16_swap_b32_e32 v202, v204
	v_permlane16_swap_b32_e32 v203, v205
	v_permlane16_swap_b32_e32 v206, v208
	v_permlane16_swap_b32_e32 v207, v209
	s_nop 0
	global_store_dwordx4 v[158:159], v[202:205], off
	global_store_dwordx4 v[158:159], v[206:209], off offset:256
	v_lshl_add_u64 v[158:159], v[158:159], 0, s[16:17]
	v_mul_f32_e32 v186, 0x3fb8aa3b, v92
	v_mul_f32_e32 v187, 0x3fb8aa3b, v93
	v_mul_f32_e32 v188, 0x3fb8aa3b, v94
	v_mul_f32_e32 v189, 0x3fb8aa3b, v95
	v_mul_f32_e32 v190, 0x3fb8aa3b, v88
	v_mul_f32_e32 v191, 0x3fb8aa3b, v89
	v_mul_f32_e32 v192, 0x3fb8aa3b, v90
	v_mul_f32_e32 v193, 0x3fb8aa3b, v91
	v_exp_f32_e32 v186, v186
	v_exp_f32_e32 v187, v187
	v_exp_f32_e32 v188, v188
	v_exp_f32_e32 v189, v189
	v_exp_f32_e32 v190, v190
	v_exp_f32_e32 v191, v191
	v_exp_f32_e32 v192, v192
	v_exp_f32_e32 v193, v193
	v_add_f32_e32 v186, 1.0, v186
	v_add_f32_e32 v187, 1.0, v187
	v_add_f32_e32 v188, 1.0, v188
	v_add_f32_e32 v189, 1.0, v189
	v_add_f32_e32 v190, 1.0, v190
	v_add_f32_e32 v191, 1.0, v191
	v_add_f32_e32 v192, 1.0, v192
	v_add_f32_e32 v193, 1.0, v193
	v_rcp_f32_e32 v186, v186
	v_rcp_f32_e32 v187, v187
	v_rcp_f32_e32 v188, v188
	v_rcp_f32_e32 v189, v189
	v_rcp_f32_e32 v190, v190
	v_rcp_f32_e32 v191, v191
	v_rcp_f32_e32 v192, v192
	v_rcp_f32_e32 v193, v193
	v_pk_mul_f32 v[186:187], v[186:187], v[210:211]
	v_pk_mul_f32 v[188:189], v[188:189], v[212:213]
	v_pk_mul_f32 v[190:191], v[190:191], v[214:215]
	v_pk_mul_f32 v[192:193], v[192:193], v[216:217]
	v_cvt_pk_bf16_f32 v194, v186, v187
	v_cvt_pk_bf16_f32 v195, v188, v189
	v_cvt_pk_bf16_f32 v196, v190, v191
	v_cvt_pk_bf16_f32 v197, v192, v193
	v_mul_f32_e32 v186, 0x3fb8aa3b, v84
	v_mul_f32_e32 v187, 0x3fb8aa3b, v85
	v_mul_f32_e32 v188, 0x3fb8aa3b, v86
	v_mul_f32_e32 v189, 0x3fb8aa3b, v87
	v_mul_f32_e32 v190, 0x3fb8aa3b, v80
	v_mul_f32_e32 v191, 0x3fb8aa3b, v81
	v_mul_f32_e32 v192, 0x3fb8aa3b, v82
	v_mul_f32_e32 v193, 0x3fb8aa3b, v83
	v_exp_f32_e32 v186, v186
	v_exp_f32_e32 v187, v187
	v_exp_f32_e32 v188, v188
	v_exp_f32_e32 v189, v189
	v_exp_f32_e32 v190, v190
	v_exp_f32_e32 v191, v191
	v_exp_f32_e32 v192, v192
	v_exp_f32_e32 v193, v193
	v_add_f32_e32 v186, 1.0, v186
	v_add_f32_e32 v187, 1.0, v187
	v_add_f32_e32 v188, 1.0, v188
	v_add_f32_e32 v189, 1.0, v189
	v_add_f32_e32 v190, 1.0, v190
	v_add_f32_e32 v191, 1.0, v191
	v_add_f32_e32 v192, 1.0, v192
	v_add_f32_e32 v193, 1.0, v193
	v_rcp_f32_e32 v186, v186
	v_rcp_f32_e32 v187, v187
	v_rcp_f32_e32 v188, v188
	v_rcp_f32_e32 v189, v189
	v_rcp_f32_e32 v190, v190
	v_rcp_f32_e32 v191, v191
	v_rcp_f32_e32 v192, v192
	v_rcp_f32_e32 v193, v193
	v_pk_mul_f32 v[186:187], v[186:187], v[218:219]
	v_pk_mul_f32 v[188:189], v[188:189], v[220:221]
	v_pk_mul_f32 v[190:191], v[190:191], v[222:223]
	v_pk_mul_f32 v[192:193], v[192:193], v[224:225]
	v_cvt_pk_bf16_f32 v198, v186, v187
	v_cvt_pk_bf16_f32 v199, v188, v189
	v_cvt_pk_bf16_f32 v200, v190, v191
	v_cvt_pk_bf16_f32 v201, v192, v193
	s_nop 0
	v_permlane16_swap_b32_e32 v194, v196
	v_permlane16_swap_b32_e32 v195, v197
	v_permlane16_swap_b32_e32 v198, v200
	v_permlane16_swap_b32_e32 v199, v201
	s_nop 0
	global_store_dwordx4 v[158:159], v[194:197], off
	global_store_dwordx4 v[158:159], v[198:201], off offset:256
	v_lshl_add_u64 v[158:159], v[158:159], 0, s[16:17]
	v_mul_f32_e32 v186, 0x3fb8aa3b, v76
	v_mul_f32_e32 v187, 0x3fb8aa3b, v77
	v_mul_f32_e32 v188, 0x3fb8aa3b, v78
	v_mul_f32_e32 v189, 0x3fb8aa3b, v79
	v_mul_f32_e32 v190, 0x3fb8aa3b, v72
	v_mul_f32_e32 v191, 0x3fb8aa3b, v73
	v_mul_f32_e32 v192, 0x3fb8aa3b, v74
	v_mul_f32_e32 v193, 0x3fb8aa3b, v75
	v_exp_f32_e32 v186, v186
	v_exp_f32_e32 v187, v187
	v_exp_f32_e32 v188, v188
	v_exp_f32_e32 v189, v189
	v_exp_f32_e32 v190, v190
	v_exp_f32_e32 v191, v191
	v_exp_f32_e32 v192, v192
	v_exp_f32_e32 v193, v193
	v_add_f32_e32 v186, 1.0, v186
	v_add_f32_e32 v187, 1.0, v187
	v_add_f32_e32 v188, 1.0, v188
	v_add_f32_e32 v189, 1.0, v189
	v_add_f32_e32 v190, 1.0, v190
	v_add_f32_e32 v191, 1.0, v191
	v_add_f32_e32 v192, 1.0, v192
	v_add_f32_e32 v193, 1.0, v193
	v_rcp_f32_e32 v186, v186
	v_rcp_f32_e32 v187, v187
	v_rcp_f32_e32 v188, v188
	v_rcp_f32_e32 v189, v189
	v_rcp_f32_e32 v190, v190
	v_rcp_f32_e32 v191, v191
	v_rcp_f32_e32 v192, v192
	v_rcp_f32_e32 v193, v193
	v_pk_mul_f32 v[186:187], v[186:187], v[210:211]
	v_pk_mul_f32 v[188:189], v[188:189], v[212:213]
	v_pk_mul_f32 v[190:191], v[190:191], v[214:215]
	v_pk_mul_f32 v[192:193], v[192:193], v[216:217]
	v_cvt_pk_bf16_f32 v202, v186, v187
	v_cvt_pk_bf16_f32 v203, v188, v189
	v_cvt_pk_bf16_f32 v204, v190, v191
	v_cvt_pk_bf16_f32 v205, v192, v193
	v_mul_f32_e32 v186, 0x3fb8aa3b, v68
	v_mul_f32_e32 v187, 0x3fb8aa3b, v69
	v_mul_f32_e32 v188, 0x3fb8aa3b, v70
	v_mul_f32_e32 v189, 0x3fb8aa3b, v71
	v_mul_f32_e32 v190, 0x3fb8aa3b, v64
	v_mul_f32_e32 v191, 0x3fb8aa3b, v65
	v_mul_f32_e32 v192, 0x3fb8aa3b, v66
	v_mul_f32_e32 v193, 0x3fb8aa3b, v67
	v_exp_f32_e32 v186, v186
	v_exp_f32_e32 v187, v187
	v_exp_f32_e32 v188, v188
	v_exp_f32_e32 v189, v189
	v_exp_f32_e32 v190, v190
	v_exp_f32_e32 v191, v191
	v_exp_f32_e32 v192, v192
	v_exp_f32_e32 v193, v193
	v_add_f32_e32 v186, 1.0, v186
	v_add_f32_e32 v187, 1.0, v187
	v_add_f32_e32 v188, 1.0, v188
	v_add_f32_e32 v189, 1.0, v189
	v_add_f32_e32 v190, 1.0, v190
	v_add_f32_e32 v191, 1.0, v191
	v_add_f32_e32 v192, 1.0, v192
	v_add_f32_e32 v193, 1.0, v193
	v_rcp_f32_e32 v186, v186
	v_rcp_f32_e32 v187, v187
	v_rcp_f32_e32 v188, v188
	v_rcp_f32_e32 v189, v189
	v_rcp_f32_e32 v190, v190
	v_rcp_f32_e32 v191, v191
	v_rcp_f32_e32 v192, v192
	v_rcp_f32_e32 v193, v193
	v_pk_mul_f32 v[186:187], v[186:187], v[218:219]
	v_pk_mul_f32 v[188:189], v[188:189], v[220:221]
	v_pk_mul_f32 v[190:191], v[190:191], v[222:223]
	v_pk_mul_f32 v[192:193], v[192:193], v[224:225]
	v_cvt_pk_bf16_f32 v206, v186, v187
	v_cvt_pk_bf16_f32 v207, v188, v189
	v_cvt_pk_bf16_f32 v208, v190, v191
	v_cvt_pk_bf16_f32 v209, v192, v193
	s_nop 0
	v_permlane16_swap_b32_e32 v202, v204
	v_permlane16_swap_b32_e32 v203, v205
	v_permlane16_swap_b32_e32 v206, v208
	v_permlane16_swap_b32_e32 v207, v209
	s_nop 0
	global_store_dwordx4 v[158:159], v[202:205], off
	global_store_dwordx4 v[158:159], v[206:209], off offset:256
	v_lshl_add_u64 v[158:159], v[158:159], 0, s[18:19]
	v_mul_f32_e32 v186, 0x3fb8aa3b, v60
	v_mul_f32_e32 v187, 0x3fb8aa3b, v61
	v_mul_f32_e32 v188, 0x3fb8aa3b, v62
	v_mul_f32_e32 v189, 0x3fb8aa3b, v63
	v_mul_f32_e32 v190, 0x3fb8aa3b, v56
	v_mul_f32_e32 v191, 0x3fb8aa3b, v57
	v_mul_f32_e32 v192, 0x3fb8aa3b, v58
	v_mul_f32_e32 v193, 0x3fb8aa3b, v59
	v_exp_f32_e32 v186, v186
	v_exp_f32_e32 v187, v187
	v_exp_f32_e32 v188, v188
	v_exp_f32_e32 v189, v189
	v_exp_f32_e32 v190, v190
	v_exp_f32_e32 v191, v191
	v_exp_f32_e32 v192, v192
	v_exp_f32_e32 v193, v193
	v_add_f32_e32 v186, 1.0, v186
	v_add_f32_e32 v187, 1.0, v187
	v_add_f32_e32 v188, 1.0, v188
	v_add_f32_e32 v189, 1.0, v189
	v_add_f32_e32 v190, 1.0, v190
	v_add_f32_e32 v191, 1.0, v191
	v_add_f32_e32 v192, 1.0, v192
	v_add_f32_e32 v193, 1.0, v193
	v_rcp_f32_e32 v186, v186
	v_rcp_f32_e32 v187, v187
	v_rcp_f32_e32 v188, v188
	v_rcp_f32_e32 v189, v189
	v_rcp_f32_e32 v190, v190
	v_rcp_f32_e32 v191, v191
	v_rcp_f32_e32 v192, v192
	v_rcp_f32_e32 v193, v193
	v_pk_mul_f32 v[186:187], v[186:187], v[210:211]
	v_pk_mul_f32 v[188:189], v[188:189], v[212:213]
	v_pk_mul_f32 v[190:191], v[190:191], v[214:215]
	v_pk_mul_f32 v[192:193], v[192:193], v[216:217]
	v_cvt_pk_bf16_f32 v194, v186, v187
	v_cvt_pk_bf16_f32 v195, v188, v189
	v_cvt_pk_bf16_f32 v196, v190, v191
	v_cvt_pk_bf16_f32 v197, v192, v193
	v_mul_f32_e32 v186, 0x3fb8aa3b, v52
	v_mul_f32_e32 v187, 0x3fb8aa3b, v53
	v_mul_f32_e32 v188, 0x3fb8aa3b, v54
	v_mul_f32_e32 v189, 0x3fb8aa3b, v55
	v_mul_f32_e32 v190, 0x3fb8aa3b, v48
	v_mul_f32_e32 v191, 0x3fb8aa3b, v49
	v_mul_f32_e32 v192, 0x3fb8aa3b, v50
	v_mul_f32_e32 v193, 0x3fb8aa3b, v51
	v_exp_f32_e32 v186, v186
	v_exp_f32_e32 v187, v187
	v_exp_f32_e32 v188, v188
	v_exp_f32_e32 v189, v189
	v_exp_f32_e32 v190, v190
	v_exp_f32_e32 v191, v191
	v_exp_f32_e32 v192, v192
	v_exp_f32_e32 v193, v193
	v_add_f32_e32 v186, 1.0, v186
	v_add_f32_e32 v187, 1.0, v187
	v_add_f32_e32 v188, 1.0, v188
	v_add_f32_e32 v189, 1.0, v189
	v_add_f32_e32 v190, 1.0, v190
	v_add_f32_e32 v191, 1.0, v191
	v_add_f32_e32 v192, 1.0, v192
	v_add_f32_e32 v193, 1.0, v193
	v_rcp_f32_e32 v186, v186
	v_rcp_f32_e32 v187, v187
	v_rcp_f32_e32 v188, v188
	v_rcp_f32_e32 v189, v189
	v_rcp_f32_e32 v190, v190
	v_rcp_f32_e32 v191, v191
	v_rcp_f32_e32 v192, v192
	v_rcp_f32_e32 v193, v193
	v_pk_mul_f32 v[186:187], v[186:187], v[218:219]
	v_pk_mul_f32 v[188:189], v[188:189], v[220:221]
	v_pk_mul_f32 v[190:191], v[190:191], v[222:223]
	v_pk_mul_f32 v[192:193], v[192:193], v[224:225]
	v_cvt_pk_bf16_f32 v198, v186, v187
	v_cvt_pk_bf16_f32 v199, v188, v189
	v_cvt_pk_bf16_f32 v200, v190, v191
	v_cvt_pk_bf16_f32 v201, v192, v193
	s_nop 0
	v_permlane16_swap_b32_e32 v194, v196
	v_permlane16_swap_b32_e32 v195, v197
	v_permlane16_swap_b32_e32 v198, v200
	v_permlane16_swap_b32_e32 v199, v201
	s_nop 0
	global_store_dwordx4 v[158:159], v[194:197], off
	global_store_dwordx4 v[158:159], v[198:201], off offset:256
	v_lshl_add_u64 v[158:159], v[158:159], 0, s[16:17]
	v_mul_f32_e32 v186, 0x3fb8aa3b, v44
	v_mul_f32_e32 v187, 0x3fb8aa3b, v45
	v_mul_f32_e32 v188, 0x3fb8aa3b, v46
	v_mul_f32_e32 v189, 0x3fb8aa3b, v47
	v_mul_f32_e32 v190, 0x3fb8aa3b, v40
	v_mul_f32_e32 v191, 0x3fb8aa3b, v41
	v_mul_f32_e32 v192, 0x3fb8aa3b, v42
	v_mul_f32_e32 v193, 0x3fb8aa3b, v43
	v_exp_f32_e32 v186, v186
	v_exp_f32_e32 v187, v187
	v_exp_f32_e32 v188, v188
	v_exp_f32_e32 v189, v189
	v_exp_f32_e32 v190, v190
	v_exp_f32_e32 v191, v191
	v_exp_f32_e32 v192, v192
	v_exp_f32_e32 v193, v193
	v_add_f32_e32 v186, 1.0, v186
	v_add_f32_e32 v187, 1.0, v187
	v_add_f32_e32 v188, 1.0, v188
	v_add_f32_e32 v189, 1.0, v189
	v_add_f32_e32 v190, 1.0, v190
	v_add_f32_e32 v191, 1.0, v191
	v_add_f32_e32 v192, 1.0, v192
	v_add_f32_e32 v193, 1.0, v193
	v_rcp_f32_e32 v186, v186
	v_rcp_f32_e32 v187, v187
	v_rcp_f32_e32 v188, v188
	v_rcp_f32_e32 v189, v189
	v_rcp_f32_e32 v190, v190
	v_rcp_f32_e32 v191, v191
	v_rcp_f32_e32 v192, v192
	v_rcp_f32_e32 v193, v193
	v_pk_mul_f32 v[186:187], v[186:187], v[210:211]
	v_pk_mul_f32 v[188:189], v[188:189], v[212:213]
	v_pk_mul_f32 v[190:191], v[190:191], v[214:215]
	v_pk_mul_f32 v[192:193], v[192:193], v[216:217]
	v_cvt_pk_bf16_f32 v202, v186, v187
	v_cvt_pk_bf16_f32 v203, v188, v189
	v_cvt_pk_bf16_f32 v204, v190, v191
	v_cvt_pk_bf16_f32 v205, v192, v193
	v_mul_f32_e32 v186, 0x3fb8aa3b, v36
	v_mul_f32_e32 v187, 0x3fb8aa3b, v37
	v_mul_f32_e32 v188, 0x3fb8aa3b, v38
	v_mul_f32_e32 v189, 0x3fb8aa3b, v39
	v_mul_f32_e32 v190, 0x3fb8aa3b, v32
	v_mul_f32_e32 v191, 0x3fb8aa3b, v33
	v_mul_f32_e32 v192, 0x3fb8aa3b, v34
	v_mul_f32_e32 v193, 0x3fb8aa3b, v35
	v_exp_f32_e32 v186, v186
	v_exp_f32_e32 v187, v187
	v_exp_f32_e32 v188, v188
	v_exp_f32_e32 v189, v189
	v_exp_f32_e32 v190, v190
	v_exp_f32_e32 v191, v191
	v_exp_f32_e32 v192, v192
	v_exp_f32_e32 v193, v193
	v_add_f32_e32 v186, 1.0, v186
	v_add_f32_e32 v187, 1.0, v187
	v_add_f32_e32 v188, 1.0, v188
	v_add_f32_e32 v189, 1.0, v189
	v_add_f32_e32 v190, 1.0, v190
	v_add_f32_e32 v191, 1.0, v191
	v_add_f32_e32 v192, 1.0, v192
	v_add_f32_e32 v193, 1.0, v193
	v_rcp_f32_e32 v186, v186
	v_rcp_f32_e32 v187, v187
	v_rcp_f32_e32 v188, v188
	v_rcp_f32_e32 v189, v189
	v_rcp_f32_e32 v190, v190
	v_rcp_f32_e32 v191, v191
	v_rcp_f32_e32 v192, v192
	v_rcp_f32_e32 v193, v193
	v_pk_mul_f32 v[186:187], v[186:187], v[218:219]
	v_pk_mul_f32 v[188:189], v[188:189], v[220:221]
	v_pk_mul_f32 v[190:191], v[190:191], v[222:223]
	v_pk_mul_f32 v[192:193], v[192:193], v[224:225]
	v_cvt_pk_bf16_f32 v206, v186, v187
	v_cvt_pk_bf16_f32 v207, v188, v189
	v_cvt_pk_bf16_f32 v208, v190, v191
	v_cvt_pk_bf16_f32 v209, v192, v193
	s_nop 0
	v_permlane16_swap_b32_e32 v202, v204
	v_permlane16_swap_b32_e32 v203, v205
	v_permlane16_swap_b32_e32 v206, v208
	v_permlane16_swap_b32_e32 v207, v209
	s_nop 0
	global_store_dwordx4 v[158:159], v[202:205], off
	global_store_dwordx4 v[158:159], v[206:209], off offset:256
	v_lshl_add_u64 v[158:159], v[158:159], 0, s[16:17]
	v_mul_f32_e32 v186, 0x3fb8aa3b, v28
	v_mul_f32_e32 v187, 0x3fb8aa3b, v29
	v_mul_f32_e32 v188, 0x3fb8aa3b, v30
	v_mul_f32_e32 v189, 0x3fb8aa3b, v31
	v_mul_f32_e32 v190, 0x3fb8aa3b, v24
	v_mul_f32_e32 v191, 0x3fb8aa3b, v25
	v_mul_f32_e32 v192, 0x3fb8aa3b, v26
	v_mul_f32_e32 v193, 0x3fb8aa3b, v27
	v_exp_f32_e32 v186, v186
	v_exp_f32_e32 v187, v187
	v_exp_f32_e32 v188, v188
	v_exp_f32_e32 v189, v189
	v_exp_f32_e32 v190, v190
	v_exp_f32_e32 v191, v191
	v_exp_f32_e32 v192, v192
	v_exp_f32_e32 v193, v193
	v_add_f32_e32 v186, 1.0, v186
	v_add_f32_e32 v187, 1.0, v187
	v_add_f32_e32 v188, 1.0, v188
	v_add_f32_e32 v189, 1.0, v189
	v_add_f32_e32 v190, 1.0, v190
	v_add_f32_e32 v191, 1.0, v191
	v_add_f32_e32 v192, 1.0, v192
	v_add_f32_e32 v193, 1.0, v193
	v_rcp_f32_e32 v186, v186
	v_rcp_f32_e32 v187, v187
	v_rcp_f32_e32 v188, v188
	v_rcp_f32_e32 v189, v189
	v_rcp_f32_e32 v190, v190
	v_rcp_f32_e32 v191, v191
	v_rcp_f32_e32 v192, v192
	v_rcp_f32_e32 v193, v193
	v_pk_mul_f32 v[186:187], v[186:187], v[210:211]
	v_pk_mul_f32 v[188:189], v[188:189], v[212:213]
	v_pk_mul_f32 v[190:191], v[190:191], v[214:215]
	v_pk_mul_f32 v[192:193], v[192:193], v[216:217]
	v_cvt_pk_bf16_f32 v194, v186, v187
	v_cvt_pk_bf16_f32 v195, v188, v189
	v_cvt_pk_bf16_f32 v196, v190, v191
	v_cvt_pk_bf16_f32 v197, v192, v193
	v_mul_f32_e32 v186, 0x3fb8aa3b, v20
	v_mul_f32_e32 v187, 0x3fb8aa3b, v21
	v_mul_f32_e32 v188, 0x3fb8aa3b, v22
	v_mul_f32_e32 v189, 0x3fb8aa3b, v23
	v_mul_f32_e32 v190, 0x3fb8aa3b, v16
	v_mul_f32_e32 v191, 0x3fb8aa3b, v17
	v_mul_f32_e32 v192, 0x3fb8aa3b, v18
	v_mul_f32_e32 v193, 0x3fb8aa3b, v19
	v_exp_f32_e32 v186, v186
	v_exp_f32_e32 v187, v187
	v_exp_f32_e32 v188, v188
	v_exp_f32_e32 v189, v189
	v_exp_f32_e32 v190, v190
	v_exp_f32_e32 v191, v191
	v_exp_f32_e32 v192, v192
	v_exp_f32_e32 v193, v193
	v_add_f32_e32 v186, 1.0, v186
	v_add_f32_e32 v187, 1.0, v187
	v_add_f32_e32 v188, 1.0, v188
	v_add_f32_e32 v189, 1.0, v189
	v_add_f32_e32 v190, 1.0, v190
	v_add_f32_e32 v191, 1.0, v191
	v_add_f32_e32 v192, 1.0, v192
	v_add_f32_e32 v193, 1.0, v193
	v_rcp_f32_e32 v186, v186
	v_rcp_f32_e32 v187, v187
	v_rcp_f32_e32 v188, v188
	v_rcp_f32_e32 v189, v189
	v_rcp_f32_e32 v190, v190
	v_rcp_f32_e32 v191, v191
	v_rcp_f32_e32 v192, v192
	v_rcp_f32_e32 v193, v193
	v_pk_mul_f32 v[186:187], v[186:187], v[218:219]
	v_pk_mul_f32 v[188:189], v[188:189], v[220:221]
	v_pk_mul_f32 v[190:191], v[190:191], v[222:223]
	v_pk_mul_f32 v[192:193], v[192:193], v[224:225]
	v_cvt_pk_bf16_f32 v198, v186, v187
	v_cvt_pk_bf16_f32 v199, v188, v189
	v_cvt_pk_bf16_f32 v200, v190, v191
	v_cvt_pk_bf16_f32 v201, v192, v193
	s_nop 0
	v_permlane16_swap_b32_e32 v194, v196
	v_permlane16_swap_b32_e32 v195, v197
	v_permlane16_swap_b32_e32 v198, v200
	v_permlane16_swap_b32_e32 v199, v201
	s_nop 0
	global_store_dwordx4 v[158:159], v[194:197], off
	global_store_dwordx4 v[158:159], v[198:201], off offset:256
	v_lshl_add_u64 v[158:159], v[158:159], 0, s[16:17]
	v_mul_f32_e32 v186, 0x3fb8aa3b, v12
	v_mul_f32_e32 v187, 0x3fb8aa3b, v13
	v_mul_f32_e32 v188, 0x3fb8aa3b, v14
	v_mul_f32_e32 v189, 0x3fb8aa3b, v15
	v_mul_f32_e32 v190, 0x3fb8aa3b, v8
	v_mul_f32_e32 v191, 0x3fb8aa3b, v9
	v_mul_f32_e32 v192, 0x3fb8aa3b, v10
	v_mul_f32_e32 v193, 0x3fb8aa3b, v11
	v_exp_f32_e32 v186, v186
	v_exp_f32_e32 v187, v187
	v_exp_f32_e32 v188, v188
	v_exp_f32_e32 v189, v189
	v_exp_f32_e32 v190, v190
	v_exp_f32_e32 v191, v191
	v_exp_f32_e32 v192, v192
	v_exp_f32_e32 v193, v193
	v_add_f32_e32 v186, 1.0, v186
	v_add_f32_e32 v187, 1.0, v187
	v_add_f32_e32 v188, 1.0, v188
	v_add_f32_e32 v189, 1.0, v189
	v_add_f32_e32 v190, 1.0, v190
	v_add_f32_e32 v191, 1.0, v191
	v_add_f32_e32 v192, 1.0, v192
	v_add_f32_e32 v193, 1.0, v193
	v_rcp_f32_e32 v186, v186
	v_rcp_f32_e32 v187, v187
	v_rcp_f32_e32 v188, v188
	v_rcp_f32_e32 v189, v189
	v_rcp_f32_e32 v190, v190
	v_rcp_f32_e32 v191, v191
	v_rcp_f32_e32 v192, v192
	v_rcp_f32_e32 v193, v193
	v_pk_mul_f32 v[186:187], v[186:187], v[210:211]
	v_pk_mul_f32 v[188:189], v[188:189], v[212:213]
	v_pk_mul_f32 v[190:191], v[190:191], v[214:215]
	v_pk_mul_f32 v[192:193], v[192:193], v[216:217]
	v_cvt_pk_bf16_f32 v202, v186, v187
	v_cvt_pk_bf16_f32 v203, v188, v189
	v_cvt_pk_bf16_f32 v204, v190, v191
	v_cvt_pk_bf16_f32 v205, v192, v193
	v_mul_f32_e32 v186, 0x3fb8aa3b, v4
	v_mul_f32_e32 v187, 0x3fb8aa3b, v5
	v_mul_f32_e32 v188, 0x3fb8aa3b, v6
	v_mul_f32_e32 v189, 0x3fb8aa3b, v7
	v_mul_f32_e32 v190, 0x3fb8aa3b, v0
	v_mul_f32_e32 v191, 0x3fb8aa3b, v1
	v_mul_f32_e32 v192, 0x3fb8aa3b, v2
	v_mul_f32_e32 v193, 0x3fb8aa3b, v3
	v_exp_f32_e32 v186, v186
	v_exp_f32_e32 v187, v187
	v_exp_f32_e32 v188, v188
	v_exp_f32_e32 v189, v189
	v_exp_f32_e32 v190, v190
	v_exp_f32_e32 v191, v191
	v_exp_f32_e32 v192, v192
	v_exp_f32_e32 v193, v193
	v_add_f32_e32 v186, 1.0, v186
	v_add_f32_e32 v187, 1.0, v187
	v_add_f32_e32 v188, 1.0, v188
	v_add_f32_e32 v189, 1.0, v189
	v_add_f32_e32 v190, 1.0, v190
	v_add_f32_e32 v191, 1.0, v191
	v_add_f32_e32 v192, 1.0, v192
	v_add_f32_e32 v193, 1.0, v193
	v_rcp_f32_e32 v186, v186
	v_rcp_f32_e32 v187, v187
	v_rcp_f32_e32 v188, v188
	v_rcp_f32_e32 v189, v189
	v_rcp_f32_e32 v190, v190
	v_rcp_f32_e32 v191, v191
	v_rcp_f32_e32 v192, v192
	v_rcp_f32_e32 v193, v193
	v_pk_mul_f32 v[186:187], v[186:187], v[218:219]
	v_pk_mul_f32 v[188:189], v[188:189], v[220:221]
	v_pk_mul_f32 v[190:191], v[190:191], v[222:223]
	v_pk_mul_f32 v[192:193], v[192:193], v[224:225]
	v_cvt_pk_bf16_f32 v206, v186, v187
	v_cvt_pk_bf16_f32 v207, v188, v189
	v_cvt_pk_bf16_f32 v208, v190, v191
	v_cvt_pk_bf16_f32 v209, v192, v193
	s_nop 0
	v_permlane16_swap_b32_e32 v202, v204
	v_permlane16_swap_b32_e32 v203, v205
	v_permlane16_swap_b32_e32 v206, v208
	v_permlane16_swap_b32_e32 v207, v209
	s_nop 0
	global_store_dwordx4 v[158:159], v[202:205], off
	global_store_dwordx4 v[158:159], v[206:209], off offset:256
	s_branch .LBB0_224
.Lepi_hg_copy:
	v_cvt_pk_bf16_f32 v194, v124, v125
	v_cvt_pk_bf16_f32 v195, v126, v127
	v_cvt_pk_bf16_f32 v196, v120, v121
	v_cvt_pk_bf16_f32 v197, v122, v123
	v_cvt_pk_bf16_f32 v198, v116, v117
	v_cvt_pk_bf16_f32 v199, v118, v119
	v_cvt_pk_bf16_f32 v200, v112, v113
	v_cvt_pk_bf16_f32 v201, v114, v115
	s_nop 0
	v_permlane16_swap_b32_e32 v194, v196
	v_permlane16_swap_b32_e32 v195, v197
	v_permlane16_swap_b32_e32 v198, v200
	v_permlane16_swap_b32_e32 v199, v201
	s_nop 0
	global_store_dwordx4 v[158:159], v[194:197], off
	global_store_dwordx4 v[158:159], v[198:201], off offset:256
	v_lshl_add_u64 v[158:159], v[158:159], 0, s[16:17]
	v_cvt_pk_bf16_f32 v202, v108, v109
	v_cvt_pk_bf16_f32 v203, v110, v111
	v_cvt_pk_bf16_f32 v204, v104, v105
	v_cvt_pk_bf16_f32 v205, v106, v107
	v_cvt_pk_bf16_f32 v206, v100, v101
	v_cvt_pk_bf16_f32 v207, v102, v103
	v_cvt_pk_bf16_f32 v208, v96, v97
	v_cvt_pk_bf16_f32 v209, v98, v99
	s_nop 0
	v_permlane16_swap_b32_e32 v202, v204
	v_permlane16_swap_b32_e32 v203, v205
	v_permlane16_swap_b32_e32 v206, v208
	v_permlane16_swap_b32_e32 v207, v209
	s_nop 0
	global_store_dwordx4 v[158:159], v[202:205], off
	global_store_dwordx4 v[158:159], v[206:209], off offset:256
	v_lshl_add_u64 v[158:159], v[158:159], 0, s[16:17]
	v_cvt_pk_bf16_f32 v194, v92, v93
	v_cvt_pk_bf16_f32 v195, v94, v95
	v_cvt_pk_bf16_f32 v196, v88, v89
	v_cvt_pk_bf16_f32 v197, v90, v91
	v_cvt_pk_bf16_f32 v198, v84, v85
	v_cvt_pk_bf16_f32 v199, v86, v87
	v_cvt_pk_bf16_f32 v200, v80, v81
	v_cvt_pk_bf16_f32 v201, v82, v83
	s_nop 0
	v_permlane16_swap_b32_e32 v194, v196
	v_permlane16_swap_b32_e32 v195, v197
	v_permlane16_swap_b32_e32 v198, v200
	v_permlane16_swap_b32_e32 v199, v201
	s_nop 0
	global_store_dwordx4 v[158:159], v[194:197], off
	global_store_dwordx4 v[158:159], v[198:201], off offset:256
	v_lshl_add_u64 v[158:159], v[158:159], 0, s[16:17]
	v_cvt_pk_bf16_f32 v202, v76, v77
	v_cvt_pk_bf16_f32 v203, v78, v79
	v_cvt_pk_bf16_f32 v204, v72, v73
	v_cvt_pk_bf16_f32 v205, v74, v75
	v_cvt_pk_bf16_f32 v206, v68, v69
	v_cvt_pk_bf16_f32 v207, v70, v71
	v_cvt_pk_bf16_f32 v208, v64, v65
	v_cvt_pk_bf16_f32 v209, v66, v67
	s_nop 0
	v_permlane16_swap_b32_e32 v202, v204
	v_permlane16_swap_b32_e32 v203, v205
	v_permlane16_swap_b32_e32 v206, v208
	v_permlane16_swap_b32_e32 v207, v209
	s_nop 0
	global_store_dwordx4 v[158:159], v[202:205], off
	global_store_dwordx4 v[158:159], v[206:209], off offset:256
	v_lshl_add_u64 v[158:159], v[158:159], 0, s[18:19]
	v_cvt_pk_bf16_f32 v194, v60, v61
	v_cvt_pk_bf16_f32 v195, v62, v63
	v_cvt_pk_bf16_f32 v196, v56, v57
	v_cvt_pk_bf16_f32 v197, v58, v59
	v_cvt_pk_bf16_f32 v198, v52, v53
	v_cvt_pk_bf16_f32 v199, v54, v55
	v_cvt_pk_bf16_f32 v200, v48, v49
	v_cvt_pk_bf16_f32 v201, v50, v51
	s_nop 0
	v_permlane16_swap_b32_e32 v194, v196
	v_permlane16_swap_b32_e32 v195, v197
	v_permlane16_swap_b32_e32 v198, v200
	v_permlane16_swap_b32_e32 v199, v201
	s_nop 0
	global_store_dwordx4 v[158:159], v[194:197], off
	global_store_dwordx4 v[158:159], v[198:201], off offset:256
	v_lshl_add_u64 v[158:159], v[158:159], 0, s[16:17]
	v_cvt_pk_bf16_f32 v202, v44, v45
	v_cvt_pk_bf16_f32 v203, v46, v47
	v_cvt_pk_bf16_f32 v204, v40, v41
	v_cvt_pk_bf16_f32 v205, v42, v43
	v_cvt_pk_bf16_f32 v206, v36, v37
	v_cvt_pk_bf16_f32 v207, v38, v39
	v_cvt_pk_bf16_f32 v208, v32, v33
	v_cvt_pk_bf16_f32 v209, v34, v35
	s_nop 0
	v_permlane16_swap_b32_e32 v202, v204
	v_permlane16_swap_b32_e32 v203, v205
	v_permlane16_swap_b32_e32 v206, v208
	v_permlane16_swap_b32_e32 v207, v209
	s_nop 0
	global_store_dwordx4 v[158:159], v[202:205], off
	global_store_dwordx4 v[158:159], v[206:209], off offset:256
	v_lshl_add_u64 v[158:159], v[158:159], 0, s[16:17]
	v_cvt_pk_bf16_f32 v194, v28, v29
	v_cvt_pk_bf16_f32 v195, v30, v31
	v_cvt_pk_bf16_f32 v196, v24, v25
	v_cvt_pk_bf16_f32 v197, v26, v27
	v_cvt_pk_bf16_f32 v198, v20, v21
	v_cvt_pk_bf16_f32 v199, v22, v23
	v_cvt_pk_bf16_f32 v200, v16, v17
	v_cvt_pk_bf16_f32 v201, v18, v19
	s_nop 0
	v_permlane16_swap_b32_e32 v194, v196
	v_permlane16_swap_b32_e32 v195, v197
	v_permlane16_swap_b32_e32 v198, v200
	v_permlane16_swap_b32_e32 v199, v201
	s_nop 0
	global_store_dwordx4 v[158:159], v[194:197], off
	global_store_dwordx4 v[158:159], v[198:201], off offset:256
	v_lshl_add_u64 v[158:159], v[158:159], 0, s[16:17]
	v_cvt_pk_bf16_f32 v202, v12, v13
	v_cvt_pk_bf16_f32 v203, v14, v15
	v_cvt_pk_bf16_f32 v204, v8, v9
	v_cvt_pk_bf16_f32 v205, v10, v11
	v_cvt_pk_bf16_f32 v206, v4, v5
	v_cvt_pk_bf16_f32 v207, v6, v7
	v_cvt_pk_bf16_f32 v208, v0, v1
	v_cvt_pk_bf16_f32 v209, v2, v3
	s_nop 0
	v_permlane16_swap_b32_e32 v202, v204
	v_permlane16_swap_b32_e32 v203, v205
	v_permlane16_swap_b32_e32 v206, v208
	v_permlane16_swap_b32_e32 v207, v209
	s_nop 0
	global_store_dwordx4 v[158:159], v[202:205], off
	global_store_dwordx4 v[158:159], v[206:209], off offset:256
	s_branch .LBB0_224
.Lepi_hg_slow:
	s_ashr_i32 s18, s2, 2
	s_cmp_gt_u32 s2, 3
	s_cselect_b64 s[4:5], -1, 0
	s_cmp_lg_u32 s18, 3
	s_cselect_b64 s[6:7], -1, 0
	s_and_b64 s[16:17], s[4:5], s[6:7]
	v_lshl_add_u32 v185, s20, 8, v143
	s_cmp_eq_u32 s18, 1
	v_lshl_or_b32 v156, s2, 8, v166
	s_cselect_b64 s[6:7], -1, 0
	v_cmp_gt_i32_e32 vcc, s39, v185
	s_and_saveexec_b64 s[18:19], vcc
	s_cbranch_execz .LBB0_259
	s_mov_b64 s[4:5], -1
	s_and_b64 vcc, exec, s[16:17]
	s_cbranch_vccz .LBB0_238
	s_andn2_b64 vcc, exec, s[6:7]
	v_mov_b32_e32 v159, v127
	v_mov_b32_e32 v158, v126
	v_mov_b32_e32 v161, v125
	v_mov_b32_e32 v160, v124
	s_cbranch_vccnz .LBB0_237
	v_and_b32_e32 v157, 0x36c, v156
	v_lshlrev_b32_e32 v157, 2, v157
	global_load_dwordx4 v[186:189], v157, s[98:99]
	v_mul_f32_e32 v157, 0x3fb8aa3b, v124
	v_mul_f32_e32 v158, 0x3fb8aa3b, v125
	v_mul_f32_e32 v159, 0x3fb8aa3b, v126
	v_mul_f32_e32 v160, 0x3fb8aa3b, v127
	v_exp_f32_e32 v157, v157
	v_exp_f32_e32 v158, v158
	v_exp_f32_e32 v159, v159
	v_exp_f32_e32 v160, v160
	v_add_f32_e32 v157, 1.0, v157
	v_add_f32_e32 v161, 1.0, v158
	v_add_f32_e32 v190, 1.0, v159
	v_add_f32_e32 v160, 1.0, v160
	v_rcp_f32_e32 v158, v157
	v_rcp_f32_e32 v159, v161
	v_rcp_f32_e32 v190, v190
	v_rcp_f32_e32 v191, v160
	s_waitcnt vmcnt(0)
	v_pk_mul_f32 v[160:161], v[158:159], v[186:187]
	v_pk_mul_f32 v[158:159], v[190:191], v[188:189]

.LBB0_737:
	ds_read_b128 v[146:149], v154
	ds_read_b128 v[170:173], v155
	ds_read_b128 v[174:177], v156
	ds_read_b128 v[178:181], v157
	s_add_u32 s18, s6, 0xfff7c080
	s_addc_u32 s19, s7, -1
	s_cmp_eq_u32 s52, 28
	s_cselect_b32 s21, s17, s19
	s_cselect_b32 s20, s16, s18
	s_cselect_b32 s19, s9, s39
	s_cselect_b32 s18, s8, s38
	s_mov_b32 m0, s46
	v_lshl_add_u64 v[150:151], s[6:7], 0, v[138:139]
	ds_read_b128 v[182:185], v152
	ds_read_b128 v[186:189], v152 offset:1024
	ds_read_b128 v[190:193], v152 offset:2048
	ds_read_b128 v[194:197], v152 offset:3072
	ds_read_b128 v[198:201], v152 offset:4096
	ds_read_b128 v[202:205], v152 offset:5120
	ds_read_b128 v[206:209], v152 offset:6144
	ds_read_b128 v[210:213], v152 offset:7168
	global_load_lds_dwordx4 v[150:151], off
	v_lshl_add_u64 v[150:151], s[6:7], 0, v[140:141]
	s_mov_b32 m0, s47
	s_nop 0
	global_load_lds_dwordx4 v[150:151], off
	s_waitcnt lgkmcnt(8)
	s_barrier
	s_waitcnt lgkmcnt(0)
	s_setprio 1
	s_waitcnt lgkmcnt(0)
	v_mfma_f32_16x16x32_bf16 v[124:127], v[146:149], v[182:185], v[124:127]
	v_mfma_f32_16x16x32_bf16 v[120:123], v[174:177], v[182:185], v[120:123]
	v_mfma_f32_16x16x32_bf16 v[108:111], v[146:149], v[190:193], v[108:111]
	v_mfma_f32_16x16x32_bf16 v[104:107], v[174:177], v[190:193], v[104:107]
	v_mfma_f32_16x16x32_bf16 v[92:95], v[146:149], v[198:201], v[92:95]
	v_mfma_f32_16x16x32_bf16 v[88:91], v[174:177], v[198:201], v[88:91]
	v_mfma_f32_16x16x32_bf16 v[76:79], v[146:149], v[206:209], v[76:79]
	v_mfma_f32_16x16x32_bf16 v[72:75], v[174:177], v[206:209], v[72:75]
	v_mfma_f32_16x16x32_bf16 v[124:127], v[170:173], v[186:189], v[124:127]
	v_mfma_f32_16x16x32_bf16 v[120:123], v[178:181], v[186:189], v[120:123]
	v_mfma_f32_16x16x32_bf16 v[108:111], v[170:173], v[194:197], v[108:111]
	v_mfma_f32_16x16x32_bf16 v[104:107], v[178:181], v[194:197], v[104:107]
	v_mfma_f32_16x16x32_bf16 v[92:95], v[170:173], v[202:205], v[92:95]
	v_mfma_f32_16x16x32_bf16 v[88:91], v[178:181], v[202:205], v[88:91]
	v_mfma_f32_16x16x32_bf16 v[76:79], v[170:173], v[210:213], v[76:79]
	v_mfma_f32_16x16x32_bf16 v[72:75], v[178:181], v[210:213], v[72:75]
	s_setprio 0
	s_barrier
	s_mov_b32 m0, s23
	v_lshl_add_u64 v[150:151], s[18:19], 0, v[130:131]
	ds_read_b128 v[214:217], v158
	ds_read_b128 v[218:221], v159
	ds_read_b128 v[222:225], v160
	ds_read_b128 v[226:229], v161
	global_load_lds_dwordx4 v[150:151], off
	v_lshl_add_u64 v[230:231], s[18:19], 0, v[132:133]
	s_mov_b32 m0, s24
	s_nop 0
	global_load_lds_dwordx4 v[230:231], off
	s_barrier
	s_waitcnt lgkmcnt(0)
	s_setprio 1
	s_waitcnt lgkmcnt(0)
	v_mfma_f32_16x16x32_bf16 v[116:119], v[214:217], v[182:185], v[116:119]
	v_mfma_f32_16x16x32_bf16 v[112:115], v[222:225], v[182:185], v[112:115]
	v_mfma_f32_16x16x32_bf16 v[100:103], v[214:217], v[190:193], v[100:103]
	v_mfma_f32_16x16x32_bf16 v[96:99], v[222:225], v[190:193], v[96:99]
	v_mfma_f32_16x16x32_bf16 v[84:87], v[214:217], v[198:201], v[84:87]
	v_mfma_f32_16x16x32_bf16 v[80:83], v[222:225], v[198:201], v[80:83]
	v_mfma_f32_16x16x32_bf16 v[68:71], v[214:217], v[206:209], v[68:71]
	v_mfma_f32_16x16x32_bf16 v[64:67], v[222:225], v[206:209], v[64:67]
	v_mfma_f32_16x16x32_bf16 v[116:119], v[218:221], v[186:189], v[116:119]
	v_mfma_f32_16x16x32_bf16 v[112:115], v[226:229], v[186:189], v[112:115]
	v_mfma_f32_16x16x32_bf16 v[100:103], v[218:221], v[194:197], v[100:103]
	v_mfma_f32_16x16x32_bf16 v[96:99], v[226:229], v[194:197], v[96:99]
	v_mfma_f32_16x16x32_bf16 v[84:87], v[218:221], v[202:205], v[84:87]
	v_mfma_f32_16x16x32_bf16 v[80:83], v[226:229], v[202:205], v[80:83]
	v_mfma_f32_16x16x32_bf16 v[68:71], v[218:221], v[210:213], v[68:71]
	v_mfma_f32_16x16x32_bf16 v[64:67], v[226:229], v[210:213], v[64:67]
	s_setprio 0
	s_mov_b32 m0, s22
	v_lshl_add_u64 v[232:233], s[20:21], 0, v[130:131]
	s_barrier
	ds_read_b128 v[182:185], v152 offset:16384
	ds_read_b128 v[186:189], v152 offset:17408
	ds_read_b128 v[190:193], v152 offset:18432
	ds_read_b128 v[194:197], v152 offset:19456
	ds_read_b128 v[198:201], v152 offset:20480
	ds_read_b128 v[202:205], v152 offset:21504
	ds_read_b128 v[206:209], v152 offset:22528
	ds_read_b128 v[210:213], v152 offset:23552
	global_load_lds_dwordx4 v[232:233], off
	v_lshl_add_u64 v[234:235], s[20:21], 0, v[132:133]
	s_mov_b32 m0, s25
	s_nop 0
	global_load_lds_dwordx4 v[234:235], off
	s_barrier
	s_waitcnt lgkmcnt(0)
	s_setprio 1
	s_waitcnt lgkmcnt(0)
	v_mfma_f32_16x16x32_bf16 v[60:63], v[146:149], v[182:185], v[60:63]
	v_mfma_f32_16x16x32_bf16 v[56:59], v[174:177], v[182:185], v[56:59]
	v_mfma_f32_16x16x32_bf16 v[44:47], v[146:149], v[190:193], v[44:47]
	v_mfma_f32_16x16x32_bf16 v[40:43], v[174:177], v[190:193], v[40:43]
	v_mfma_f32_16x16x32_bf16 v[28:31], v[146:149], v[198:201], v[28:31]
	v_mfma_f32_16x16x32_bf16 v[24:27], v[174:177], v[198:201], v[24:27]
	v_mfma_f32_16x16x32_bf16 v[12:15], v[146:149], v[206:209], v[12:15]
	v_mfma_f32_16x16x32_bf16 v[8:11], v[174:177], v[206:209], v[8:11]
	v_mfma_f32_16x16x32_bf16 v[60:63], v[170:173], v[186:189], v[60:63]
	v_mfma_f32_16x16x32_bf16 v[56:59], v[178:181], v[186:189], v[56:59]
	v_mfma_f32_16x16x32_bf16 v[44:47], v[170:173], v[194:197], v[44:47]
	v_mfma_f32_16x16x32_bf16 v[40:43], v[178:181], v[194:197], v[40:43]
	v_mfma_f32_16x16x32_bf16 v[28:31], v[170:173], v[202:205], v[28:31]
	v_mfma_f32_16x16x32_bf16 v[24:27], v[178:181], v[202:205], v[24:27]
	v_mfma_f32_16x16x32_bf16 v[12:15], v[170:173], v[210:213], v[12:15]
	v_mfma_f32_16x16x32_bf16 v[8:11], v[178:181], v[210:213], v[8:11]
	s_setprio 0
	s_barrier
	s_add_u32 s54, s18, 0x84000
	s_addc_u32 s55, s19, 0
	s_mov_b32 m0, s26
	v_lshl_add_u64 v[146:147], s[54:55], 0, v[130:131]
	global_load_lds_dwordx4 v[146:147], off
	v_lshl_add_u64 v[146:147], s[54:55], 0, v[132:133]
	s_mov_b32 m0, s27
	s_nop 0
	global_load_lds_dwordx4 v[146:147], off
	s_waitcnt vmcnt(6)
	s_barrier
	s_setprio 1
	v_mfma_f32_16x16x32_bf16 v[52:55], v[214:217], v[182:185], v[52:55]
	v_mfma_f32_16x16x32_bf16 v[48:51], v[222:225], v[182:185], v[48:51]
	v_mfma_f32_16x16x32_bf16 v[36:39], v[214:217], v[190:193], v[36:39]
	v_mfma_f32_16x16x32_bf16 v[32:35], v[222:225], v[190:193], v[32:35]
	v_mfma_f32_16x16x32_bf16 v[20:23], v[214:217], v[198:201], v[20:23]
	v_mfma_f32_16x16x32_bf16 v[16:19], v[222:225], v[198:201], v[16:19]
	v_mfma_f32_16x16x32_bf16 v[4:7], v[214:217], v[206:209], v[4:7]
	v_mfma_f32_16x16x32_bf16 v[0:3], v[222:225], v[206:209], v[0:3]
	v_mfma_f32_16x16x32_bf16 v[52:55], v[218:221], v[186:189], v[52:55]
	v_mfma_f32_16x16x32_bf16 v[48:51], v[226:229], v[186:189], v[48:51]
	v_mfma_f32_16x16x32_bf16 v[36:39], v[218:221], v[194:197], v[36:39]
	v_mfma_f32_16x16x32_bf16 v[32:35], v[226:229], v[194:197], v[32:35]
	v_mfma_f32_16x16x32_bf16 v[20:23], v[218:221], v[202:205], v[20:23]
	v_mfma_f32_16x16x32_bf16 v[16:19], v[226:229], v[202:205], v[16:19]
	v_mfma_f32_16x16x32_bf16 v[4:7], v[218:221], v[210:213], v[4:7]
	v_mfma_f32_16x16x32_bf16 v[0:3], v[226:229], v[210:213], v[0:3]
	s_setprio 0
	s_barrier
	ds_read_b128 v[146:149], v162
	ds_read_b128 v[170:173], v163
	ds_read_b128 v[174:177], v164
	ds_read_b128 v[178:181], v165
	s_add_u32 s20, s20, 0x84000
	s_addc_u32 s21, s21, 0
	s_mov_b32 m0, s28
	v_lshl_add_u64 v[214:215], s[20:21], 0, v[130:131]
	ds_read_b128 v[182:185], v152 offset:32768
	ds_read_b128 v[186:189], v152 offset:33792
	ds_read_b128 v[190:193], v152 offset:34816
	ds_read_b128 v[194:197], v152 offset:35840
	ds_read_b128 v[198:201], v152 offset:36864
	ds_read_b128 v[202:205], v152 offset:37888
	ds_read_b128 v[206:209], v152 offset:38912
	ds_read_b128 v[210:213], v152 offset:39936
	global_load_lds_dwordx4 v[214:215], off
	v_lshl_add_u64 v[214:215], s[20:21], 0, v[132:133]
	s_mov_b32 m0, s29
	s_nop 0
	global_load_lds_dwordx4 v[214:215], off
	s_waitcnt lgkmcnt(8)
	s_barrier
	s_waitcnt lgkmcnt(0)
	s_setprio 1
	s_waitcnt lgkmcnt(0)
	v_mfma_f32_16x16x32_bf16 v[124:127], v[146:149], v[182:185], v[124:127]
	v_mfma_f32_16x16x32_bf16 v[120:123], v[174:177], v[182:185], v[120:123]
	v_mfma_f32_16x16x32_bf16 v[108:111], v[146:149], v[190:193], v[108:111]
	v_mfma_f32_16x16x32_bf16 v[104:107], v[174:177], v[190:193], v[104:107]
	v_mfma_f32_16x16x32_bf16 v[92:95], v[146:149], v[198:201], v[92:95]
	v_mfma_f32_16x16x32_bf16 v[88:91], v[174:177], v[198:201], v[88:91]
	v_mfma_f32_16x16x32_bf16 v[76:79], v[146:149], v[206:209], v[76:79]
	v_mfma_f32_16x16x32_bf16 v[72:75], v[174:177], v[206:209], v[72:75]
	v_mfma_f32_16x16x32_bf16 v[124:127], v[170:173], v[186:189], v[124:127]
	v_mfma_f32_16x16x32_bf16 v[120:123], v[178:181], v[186:189], v[120:123]
	v_mfma_f32_16x16x32_bf16 v[108:111], v[170:173], v[194:197], v[108:111]
	v_mfma_f32_16x16x32_bf16 v[104:107], v[178:181], v[194:197], v[104:107]
	v_mfma_f32_16x16x32_bf16 v[92:95], v[170:173], v[202:205], v[92:95]
	v_mfma_f32_16x16x32_bf16 v[88:91], v[178:181], v[202:205], v[88:91]
	v_mfma_f32_16x16x32_bf16 v[76:79], v[170:173], v[210:213], v[76:79]
	v_mfma_f32_16x16x32_bf16 v[72:75], v[178:181], v[210:213], v[72:75]
	s_setprio 0
	s_barrier
	s_mov_b32 m0, s31
	v_lshl_add_u64 v[150:151], v[150:151], 0, s[12:13]
	ds_read_b128 v[214:217], v166
	ds_read_b128 v[218:221], v167
	ds_read_b128 v[222:225], v168
	ds_read_b128 v[226:229], v169
	global_load_lds_dwordx4 v[150:151], off
	v_lshl_add_u64 v[150:151], v[230:231], 0, s[12:13]
	s_mov_b32 m0, s33
	s_nop 0
	global_load_lds_dwordx4 v[150:151], off
	s_barrier
	s_waitcnt lgkmcnt(0)
	s_setprio 1
	s_waitcnt lgkmcnt(0)
	v_mfma_f32_16x16x32_bf16 v[116:119], v[214:217], v[182:185], v[116:119]
	v_mfma_f32_16x16x32_bf16 v[112:115], v[222:225], v[182:185], v[112:115]
	v_mfma_f32_16x16x32_bf16 v[100:103], v[214:217], v[190:193], v[100:103]
	v_mfma_f32_16x16x32_bf16 v[96:99], v[222:225], v[190:193], v[96:99]
	v_mfma_f32_16x16x32_bf16 v[84:87], v[214:217], v[198:201], v[84:87]
	v_mfma_f32_16x16x32_bf16 v[80:83], v[222:225], v[198:201], v[80:83]
	v_mfma_f32_16x16x32_bf16 v[68:71], v[214:217], v[206:209], v[68:71]
	v_mfma_f32_16x16x32_bf16 v[64:67], v[222:225], v[206:209], v[64:67]
	v_mfma_f32_16x16x32_bf16 v[116:119], v[218:221], v[186:189], v[116:119]
	v_mfma_f32_16x16x32_bf16 v[112:115], v[226:229], v[186:189], v[112:115]
	v_mfma_f32_16x16x32_bf16 v[100:103], v[218:221], v[194:197], v[100:103]
	v_mfma_f32_16x16x32_bf16 v[96:99], v[226:229], v[194:197], v[96:99]
	v_mfma_f32_16x16x32_bf16 v[84:87], v[218:221], v[202:205], v[84:87]
	v_mfma_f32_16x16x32_bf16 v[80:83], v[226:229], v[202:205], v[80:83]
	v_mfma_f32_16x16x32_bf16 v[68:71], v[218:221], v[210:213], v[68:71]
	v_mfma_f32_16x16x32_bf16 v[64:67], v[226:229], v[210:213], v[64:67]
	s_setprio 0
	s_mov_b32 m0, s34
	v_lshl_add_u64 v[150:151], v[232:233], 0, s[12:13]
	s_barrier
	ds_read_b128 v[182:185], v152 offset:49152
	ds_read_b128 v[186:189], v152 offset:50176
	ds_read_b128 v[190:193], v152 offset:51200
	ds_read_b128 v[194:197], v152 offset:52224
	ds_read_b128 v[198:201], v152 offset:53248
	ds_read_b128 v[202:205], v152 offset:54272
	ds_read_b128 v[206:209], v152 offset:55296
	ds_read_b128 v[210:213], v152 offset:56320
	global_load_lds_dwordx4 v[150:151], off
	v_lshl_add_u64 v[150:151], v[234:235], 0, s[12:13]
	s_mov_b32 m0, s35
	s_nop 0
	global_load_lds_dwordx4 v[150:151], off
	s_barrier
	s_waitcnt lgkmcnt(0)
	s_setprio 1
	s_waitcnt lgkmcnt(0)
	v_mfma_f32_16x16x32_bf16 v[60:63], v[146:149], v[182:185], v[60:63]
	v_mfma_f32_16x16x32_bf16 v[56:59], v[174:177], v[182:185], v[56:59]
	v_mfma_f32_16x16x32_bf16 v[44:47], v[146:149], v[190:193], v[44:47]
	v_mfma_f32_16x16x32_bf16 v[40:43], v[174:177], v[190:193], v[40:43]
	v_mfma_f32_16x16x32_bf16 v[28:31], v[146:149], v[198:201], v[28:31]
	v_mfma_f32_16x16x32_bf16 v[24:27], v[174:177], v[198:201], v[24:27]
	v_mfma_f32_16x16x32_bf16 v[12:15], v[146:149], v[206:209], v[12:15]
	v_mfma_f32_16x16x32_bf16 v[8:11], v[174:177], v[206:209], v[8:11]
	v_mfma_f32_16x16x32_bf16 v[60:63], v[170:173], v[186:189], v[60:63]
	v_mfma_f32_16x16x32_bf16 v[56:59], v[178:181], v[186:189], v[56:59]
	v_mfma_f32_16x16x32_bf16 v[44:47], v[170:173], v[194:197], v[44:47]
	v_mfma_f32_16x16x32_bf16 v[40:43], v[178:181], v[194:197], v[40:43]
	v_mfma_f32_16x16x32_bf16 v[28:31], v[170:173], v[202:205], v[28:31]
	v_mfma_f32_16x16x32_bf16 v[24:27], v[178:181], v[202:205], v[24:27]
	v_mfma_f32_16x16x32_bf16 v[12:15], v[170:173], v[210:213], v[12:15]
	v_mfma_f32_16x16x32_bf16 v[8:11], v[178:181], v[210:213], v[8:11]
	s_setprio 0
	s_barrier
	s_add_u32 s18, s18, 0x84080
	s_addc_u32 s19, s19, 0
	s_mov_b32 m0, s40
	v_lshl_add_u64 v[146:147], s[18:19], 0, v[130:131]
	global_load_lds_dwordx4 v[146:147], off
	v_lshl_add_u64 v[146:147], s[18:19], 0, v[132:133]
	s_mov_b32 m0, s41
	s_nop 0
	global_load_lds_dwordx4 v[146:147], off
	s_waitcnt vmcnt(6)
	s_barrier
	s_setprio 1
	v_mfma_f32_16x16x32_bf16 v[52:55], v[214:217], v[182:185], v[52:55]
	v_mfma_f32_16x16x32_bf16 v[48:51], v[222:225], v[182:185], v[48:51]
	v_mfma_f32_16x16x32_bf16 v[36:39], v[214:217], v[190:193], v[36:39]
	v_mfma_f32_16x16x32_bf16 v[32:35], v[222:225], v[190:193], v[32:35]
	v_mfma_f32_16x16x32_bf16 v[20:23], v[214:217], v[198:201], v[20:23]
	v_mfma_f32_16x16x32_bf16 v[16:19], v[222:225], v[198:201], v[16:19]
	v_mfma_f32_16x16x32_bf16 v[4:7], v[214:217], v[206:209], v[4:7]
	v_mfma_f32_16x16x32_bf16 v[0:3], v[222:225], v[206:209], v[0:3]
	v_mfma_f32_16x16x32_bf16 v[52:55], v[218:221], v[186:189], v[52:55]
	v_mfma_f32_16x16x32_bf16 v[48:51], v[226:229], v[186:189], v[48:51]
	v_mfma_f32_16x16x32_bf16 v[36:39], v[218:221], v[194:197], v[36:39]
	v_mfma_f32_16x16x32_bf16 v[32:35], v[226:229], v[194:197], v[32:35]
	v_mfma_f32_16x16x32_bf16 v[20:23], v[218:221], v[202:205], v[20:23]
	v_mfma_f32_16x16x32_bf16 v[16:19], v[226:229], v[202:205], v[16:19]
	v_mfma_f32_16x16x32_bf16 v[4:7], v[218:221], v[210:213], v[4:7]
	v_mfma_f32_16x16x32_bf16 v[0:3], v[226:229], v[210:213], v[0:3]
	s_setprio 0
	s_add_i32 s52, s52, 2
	s_add_u32 s6, s6, 0x100
	s_addc_u32 s7, s7, 0
	s_add_u32 s38, s38, 0x100
	s_addc_u32 s39, s39, 0
	s_cmp_gt_u32 s52, 29
	s_barrier
	s_cbranch_scc0 .LBB0_737
	s_cmp_eq_u32 s37, 0
	s_cbranch_scc1 .Lepi_out_slow
	s_cmp_eq_u32 s37, 64
	s_cbranch_scc1 .Lepi_out_slow
	s_cmp_lt_u32 s37, 0x88
	s_cbranch_scc0 .Lepi_out_slow
	s_lshl_b32 s6, s37, 8
	s_add_i32 s18, s6, s30
	s_cmp_lt_u32 s37, 64
	s_cselect_b32 s19, 16, 32
	s_sub_i32 s19, s18, s19
	v_add_u32_e32 v146, s19, v134
	v_add_u32_e32 v188, s18, v134
	v_lshlrev_b32_e32 v147, 12, v146
	v_lshlrev_b32_e32 v188, 2, v188
	v_lshrrev_b32_e32 v148, 2, v153
	v_and_b32_e32 v149, 1, v148
	v_bfe_u32 v150, v148, 1, 1
	v_and_b32_e32 v148, 0x60, v153
	v_lshlrev_b32_e32 v148, 1, v148
	v_lshl_add_u32 v148, v149, 5, v148
	v_lshl_add_u32 v148, v150, 4, v148
	s_lshl_b32 s6, s36, 9
	v_add3_u32 v147, v147, v148, s6
	v_mov_b32_e32 v151, s73
	v_add_co_u32_e32 v150, vcc, s72, v147
	v_xor_b32_e32 v186, 16, v129
	v_xor_b32_e32 v187, 32, v129
	v_addc_co_u32_e32 v151, vcc, 0, v151, vcc
	v_lshlrev_b32_e32 v186, 2, v186
	v_lshlrev_b32_e32 v187, 2, v187
	s_mov_b32 s20, 0x10000
	s_mov_b32 s21, 0
	s_mov_b32 s6, 0x50000
	s_mov_b32 s7, 0
	v_mul_f32_e32 v206, v125, v125
	v_mul_f32_e32 v207, v121, v121
	v_mul_f32_e32 v208, v117, v117
	v_mul_f32_e32 v209, v113, v113
	v_fmac_f32_e32 v206, v124, v124
	v_fmac_f32_e32 v207, v120, v120
	v_fmac_f32_e32 v208, v116, v116
	v_fmac_f32_e32 v209, v112, v112
	v_fmac_f32_e32 v206, v126, v126
	v_fmac_f32_e32 v207, v122, v122
	v_fmac_f32_e32 v208, v118, v118
	v_fmac_f32_e32 v209, v114, v114
	v_fmac_f32_e32 v206, v127, v127
	v_fmac_f32_e32 v207, v123, v123
	v_fmac_f32_e32 v208, v119, v119
	v_fmac_f32_e32 v209, v115, v115
	v_add_f32_e32 v170, v206, v207
	v_add_f32_e32 v170, v170, v208
	v_add_f32_e32 v170, v170, v209
	v_mul_f32_e32 v206, v109, v109
	v_mul_f32_e32 v207, v105, v105
	v_mul_f32_e32 v208, v101, v101
	v_mul_f32_e32 v209, v97, v97
	v_fmac_f32_e32 v206, v108, v108
	v_fmac_f32_e32 v207, v104, v104
	v_fmac_f32_e32 v208, v100, v100
	v_fmac_f32_e32 v209, v96, v96
	v_fmac_f32_e32 v206, v110, v110
	v_fmac_f32_e32 v207, v106, v106
	v_fmac_f32_e32 v208, v102, v102
	v_fmac_f32_e32 v209, v98, v98
	v_fmac_f32_e32 v206, v111, v111
	v_fmac_f32_e32 v207, v107, v107
	v_fmac_f32_e32 v208, v103, v103
	v_fmac_f32_e32 v209, v99, v99
	v_add_f32_e32 v171, v206, v207
	v_add_f32_e32 v171, v171, v208
	v_add_f32_e32 v171, v171, v209
	v_mul_f32_e32 v206, v93, v93
	v_mul_f32_e32 v207, v89, v89
	v_mul_f32_e32 v208, v85, v85
	v_mul_f32_e32 v209, v81, v81
	v_fmac_f32_e32 v206, v92, v92
	v_fmac_f32_e32 v207, v88, v88
	v_fmac_f32_e32 v208, v84, v84
	v_fmac_f32_e32 v209, v80, v80
	v_fmac_f32_e32 v206, v94, v94
	v_fmac_f32_e32 v207, v90, v90
	v_fmac_f32_e32 v208, v86, v86
	v_fmac_f32_e32 v209, v82, v82
	v_fmac_f32_e32 v206, v95, v95
	v_fmac_f32_e32 v207, v91, v91
	v_fmac_f32_e32 v208, v87, v87
	v_fmac_f32_e32 v209, v83, v83
	v_add_f32_e32 v172, v206, v207
	v_add_f32_e32 v172, v172, v208
	v_add_f32_e32 v172, v172, v209
	v_mul_f32_e32 v206, v77, v77
	v_mul_f32_e32 v207, v73, v73
	v_mul_f32_e32 v208, v69, v69
	v_mul_f32_e32 v209, v65, v65
	v_fmac_f32_e32 v206, v76, v76
	v_fmac_f32_e32 v207, v72, v72
	v_fmac_f32_e32 v208, v68, v68
	v_fmac_f32_e32 v209, v64, v64
	v_fmac_f32_e32 v206, v78, v78
	v_fmac_f32_e32 v207, v74, v74
	v_fmac_f32_e32 v208, v70, v70
	v_fmac_f32_e32 v209, v66, v66
	v_fmac_f32_e32 v206, v79, v79
	v_fmac_f32_e32 v207, v75, v75
	v_fmac_f32_e32 v208, v71, v71
	v_fmac_f32_e32 v209, v67, v67
	v_add_f32_e32 v173, v206, v207
	v_add_f32_e32 v173, v173, v208
	v_add_f32_e32 v173, v173, v209
	v_mul_f32_e32 v206, v61, v61
	v_mul_f32_e32 v207, v57, v57
	v_mul_f32_e32 v208, v53, v53
	v_mul_f32_e32 v209, v49, v49
	v_fmac_f32_e32 v206, v60, v60
	v_fmac_f32_e32 v207, v56, v56
	v_fmac_f32_e32 v208, v52, v52
	v_fmac_f32_e32 v209, v48, v48
	v_fmac_f32_e32 v206, v62, v62
	v_fmac_f32_e32 v207, v58, v58
	v_fmac_f32_e32 v208, v54, v54
	v_fmac_f32_e32 v209, v50, v50
	v_fmac_f32_e32 v206, v63, v63
	v_fmac_f32_e32 v207, v59, v59
	v_fmac_f32_e32 v208, v55, v55
	v_fmac_f32_e32 v209, v51, v51
	v_add_f32_e32 v174, v206, v207
	v_add_f32_e32 v174, v174, v208
	v_add_f32_e32 v174, v174, v209
	v_mul_f32_e32 v206, v45, v45
	v_mul_f32_e32 v207, v41, v41
	v_mul_f32_e32 v208, v37, v37
	v_mul_f32_e32 v209, v33, v33
	v_fmac_f32_e32 v206, v44, v44
	v_fmac_f32_e32 v207, v40, v40
	v_fmac_f32_e32 v208, v36, v36
	v_fmac_f32_e32 v209, v32, v32
	v_fmac_f32_e32 v206, v46, v46
	v_fmac_f32_e32 v207, v42, v42
	v_fmac_f32_e32 v208, v38, v38
	v_fmac_f32_e32 v209, v34, v34
	v_fmac_f32_e32 v206, v47, v47
	v_fmac_f32_e32 v207, v43, v43
	v_fmac_f32_e32 v208, v39, v39
	v_fmac_f32_e32 v209, v35, v35
	v_add_f32_e32 v175, v206, v207
	v_add_f32_e32 v175, v175, v208
	v_add_f32_e32 v175, v175, v209
	v_mul_f32_e32 v206, v29, v29
	v_mul_f32_e32 v207, v25, v25
	v_mul_f32_e32 v208, v21, v21
	v_mul_f32_e32 v209, v17, v17
	v_fmac_f32_e32 v206, v28, v28
	v_fmac_f32_e32 v207, v24, v24
	v_fmac_f32_e32 v208, v20, v20
	v_fmac_f32_e32 v209, v16, v16
	v_fmac_f32_e32 v206, v30, v30
	v_fmac_f32_e32 v207, v26, v26
	v_fmac_f32_e32 v208, v22, v22
	v_fmac_f32_e32 v209, v18, v18
	v_fmac_f32_e32 v206, v31, v31
	v_fmac_f32_e32 v207, v27, v27
	v_fmac_f32_e32 v208, v23, v23
	v_fmac_f32_e32 v209, v19, v19
	v_add_f32_e32 v176, v206, v207
	v_add_f32_e32 v176, v176, v208
	v_add_f32_e32 v176, v176, v209
	v_mul_f32_e32 v206, v13, v13
	v_mul_f32_e32 v207, v9, v9
	v_mul_f32_e32 v208, v5, v5
	v_mul_f32_e32 v209, v1, v1
	v_fmac_f32_e32 v206, v12, v12
	v_fmac_f32_e32 v207, v8, v8
	v_fmac_f32_e32 v208, v4, v4
	v_fmac_f32_e32 v209, v0, v0
	v_fmac_f32_e32 v206, v14, v14
	v_fmac_f32_e32 v207, v10, v10
	v_fmac_f32_e32 v208, v6, v6
	v_fmac_f32_e32 v209, v2, v2
	v_fmac_f32_e32 v206, v15, v15
	v_fmac_f32_e32 v207, v11, v11
	v_fmac_f32_e32 v208, v7, v7
	v_fmac_f32_e32 v209, v3, v3
	v_add_f32_e32 v177, v206, v207
	v_add_f32_e32 v177, v177, v208
	v_add_f32_e32 v177, v177, v209
	ds_bpermute_b32 v178, v186, v170
	ds_bpermute_b32 v179, v186, v171
	ds_bpermute_b32 v180, v186, v172
	ds_bpermute_b32 v181, v186, v173
	ds_bpermute_b32 v182, v186, v174
	ds_bpermute_b32 v183, v186, v175
	ds_bpermute_b32 v184, v186, v176
	ds_bpermute_b32 v185, v186, v177
	s_waitcnt lgkmcnt(0)
	v_add_f32_e32 v170, v170, v178
	v_add_f32_e32 v171, v171, v179
	v_add_f32_e32 v172, v172, v180
	v_add_f32_e32 v173, v173, v181
	v_add_f32_e32 v174, v174, v182
	v_add_f32_e32 v175, v175, v183
	v_add_f32_e32 v176, v176, v184
	v_add_f32_e32 v177, v177, v185
	ds_bpermute_b32 v178, v187, v170
	ds_bpermute_b32 v179, v187, v171
	ds_bpermute_b32 v180, v187, v172
	ds_bpermute_b32 v181, v187, v173
	ds_bpermute_b32 v182, v187, v174
	ds_bpermute_b32 v183, v187, v175
	ds_bpermute_b32 v184, v187, v176
	ds_bpermute_b32 v185, v187, v177
	v_cvt_pk_bf16_f32 v190, v124, v125
	v_cvt_pk_bf16_f32 v191, v126, v127
	v_cvt_pk_bf16_f32 v192, v120, v121
	v_cvt_pk_bf16_f32 v193, v122, v123
	v_cvt_pk_bf16_f32 v194, v116, v117
	v_cvt_pk_bf16_f32 v195, v118, v119
	v_cvt_pk_bf16_f32 v196, v112, v113
	v_cvt_pk_bf16_f32 v197, v114, v115
	s_nop 0
	v_permlane16_swap_b32_e32 v190, v192
	v_permlane16_swap_b32_e32 v191, v193
	v_permlane16_swap_b32_e32 v194, v196
	v_permlane16_swap_b32_e32 v195, v197
	s_nop 0
	global_store_dwordx4 v[150:151], v[190:193], off
	global_store_dwordx4 v[150:151], v[194:197], off offset:256
	v_lshl_add_u64 v[150:151], v[150:151], 0, s[20:21]
	v_cvt_pk_bf16_f32 v198, v108, v109
	v_cvt_pk_bf16_f32 v199, v110, v111
	v_cvt_pk_bf16_f32 v200, v104, v105
	v_cvt_pk_bf16_f32 v201, v106, v107
	v_cvt_pk_bf16_f32 v202, v100, v101
	v_cvt_pk_bf16_f32 v203, v102, v103
	v_cvt_pk_bf16_f32 v204, v96, v97
	v_cvt_pk_bf16_f32 v205, v98, v99
	s_nop 0
	v_permlane16_swap_b32_e32 v198, v200
	v_permlane16_swap_b32_e32 v199, v201
	v_permlane16_swap_b32_e32 v202, v204
	v_permlane16_swap_b32_e32 v203, v205
	s_nop 0
	global_store_dwordx4 v[150:151], v[198:201], off
	global_store_dwordx4 v[150:151], v[202:205], off offset:256
	v_lshl_add_u64 v[150:151], v[150:151], 0, s[20:21]
	v_cvt_pk_bf16_f32 v190, v92, v93
	v_cvt_pk_bf16_f32 v191, v94, v95
	v_cvt_pk_bf16_f32 v192, v88, v89
	v_cvt_pk_bf16_f32 v193, v90, v91
	v_cvt_pk_bf16_f32 v194, v84, v85
	v_cvt_pk_bf16_f32 v195, v86, v87
	v_cvt_pk_bf16_f32 v196, v80, v81
	v_cvt_pk_bf16_f32 v197, v82, v83
	s_nop 0
	v_permlane16_swap_b32_e32 v190, v192
	v_permlane16_swap_b32_e32 v191, v193
	v_permlane16_swap_b32_e32 v194, v196
	v_permlane16_swap_b32_e32 v195, v197
	s_nop 0
	global_store_dwordx4 v[150:151], v[190:193], off
	global_store_dwordx4 v[150:151], v[194:197], off offset:256
	v_lshl_add_u64 v[150:151], v[150:151], 0, s[20:21]
	v_cvt_pk_bf16_f32 v198, v76, v77
	v_cvt_pk_bf16_f32 v199, v78, v79
	v_cvt_pk_bf16_f32 v200, v72, v73
	v_cvt_pk_bf16_f32 v201, v74, v75
	v_cvt_pk_bf16_f32 v202, v68, v69
	v_cvt_pk_bf16_f32 v203, v70, v71
	v_cvt_pk_bf16_f32 v204, v64, v65
	v_cvt_pk_bf16_f32 v205, v66, v67
	s_nop 0
	v_permlane16_swap_b32_e32 v198, v200
	v_permlane16_swap_b32_e32 v199, v201
	v_permlane16_swap_b32_e32 v202, v204
	v_permlane16_swap_b32_e32 v203, v205
	s_nop 0
	global_store_dwordx4 v[150:151], v[198:201], off
	global_store_dwordx4 v[150:151], v[202:205], off offset:256
	v_lshl_add_u64 v[150:151], v[150:151], 0, s[6:7]
	v_cvt_pk_bf16_f32 v190, v60, v61
	v_cvt_pk_bf16_f32 v191, v62, v63
	v_cvt_pk_bf16_f32 v192, v56, v57
	v_cvt_pk_bf16_f32 v193, v58, v59
	v_cvt_pk_bf16_f32 v194, v52, v53
	v_cvt_pk_bf16_f32 v195, v54, v55
	v_cvt_pk_bf16_f32 v196, v48, v49
	v_cvt_pk_bf16_f32 v197, v50, v51
	s_nop 0
	v_permlane16_swap_b32_e32 v190, v192
	v_permlane16_swap_b32_e32 v191, v193
	v_permlane16_swap_b32_e32 v194, v196
	v_permlane16_swap_b32_e32 v195, v197
	s_nop 0
	global_store_dwordx4 v[150:151], v[190:193], off
	global_store_dwordx4 v[150:151], v[194:197], off offset:256
	v_lshl_add_u64 v[150:151], v[150:151], 0, s[20:21]
	v_cvt_pk_bf16_f32 v198, v44, v45
	v_cvt_pk_bf16_f32 v199, v46, v47
	v_cvt_pk_bf16_f32 v200, v40, v41
	v_cvt_pk_bf16_f32 v201, v42, v43
	v_cvt_pk_bf16_f32 v202, v36, v37
	v_cvt_pk_bf16_f32 v203, v38, v39
	v_cvt_pk_bf16_f32 v204, v32, v33
	v_cvt_pk_bf16_f32 v205, v34, v35
	s_nop 0
	v_permlane16_swap_b32_e32 v198, v200
	v_permlane16_swap_b32_e32 v199, v201
	v_permlane16_swap_b32_e32 v202, v204
	v_permlane16_swap_b32_e32 v203, v205
	s_nop 0
	global_store_dwordx4 v[150:151], v[198:201], off
	global_store_dwordx4 v[150:151], v[202:205], off offset:256
	v_lshl_add_u64 v[150:151], v[150:151], 0, s[20:21]
	v_cvt_pk_bf16_f32 v190, v28, v29
	v_cvt_pk_bf16_f32 v191, v30, v31
	v_cvt_pk_bf16_f32 v192, v24, v25
	v_cvt_pk_bf16_f32 v193, v26, v27
	v_cvt_pk_bf16_f32 v194, v20, v21
	v_cvt_pk_bf16_f32 v195, v22, v23
	v_cvt_pk_bf16_f32 v196, v16, v17
	v_cvt_pk_bf16_f32 v197, v18, v19
	s_nop 0
	v_permlane16_swap_b32_e32 v190, v192
	v_permlane16_swap_b32_e32 v191, v193
	v_permlane16_swap_b32_e32 v194, v196
	v_permlane16_swap_b32_e32 v195, v197
	s_nop 0
	global_store_dwordx4 v[150:151], v[190:193], off
	global_store_dwordx4 v[150:151], v[194:197], off offset:256
	v_lshl_add_u64 v[150:151], v[150:151], 0, s[20:21]
	v_cvt_pk_bf16_f32 v198, v12, v13
	v_cvt_pk_bf16_f32 v199, v14, v15
	v_cvt_pk_bf16_f32 v200, v8, v9
	v_cvt_pk_bf16_f32 v201, v10, v11
	v_cvt_pk_bf16_f32 v202, v4, v5
	v_cvt_pk_bf16_f32 v203, v6, v7
	v_cvt_pk_bf16_f32 v204, v0, v1
	v_cvt_pk_bf16_f32 v205, v2, v3
	s_nop 0
	v_permlane16_swap_b32_e32 v198, v200
	v_permlane16_swap_b32_e32 v199, v201
	v_permlane16_swap_b32_e32 v202, v204
	v_permlane16_swap_b32_e32 v203, v205
	s_nop 0
	global_store_dwordx4 v[150:151], v[198:201], off
	global_store_dwordx4 v[150:151], v[202:205], off offset:256
	s_waitcnt lgkmcnt(0)
	v_add_f32_e32 v170, v170, v178
	v_add_f32_e32 v171, v171, v179
	v_add_f32_e32 v172, v172, v180
	v_add_f32_e32 v173, v173, v181
	v_add_f32_e32 v174, v174, v182
	v_add_f32_e32 v175, v175, v183
	v_add_f32_e32 v176, v176, v184
	v_add_f32_e32 v177, v177, v185
	s_mov_b64 exec, s[10:11]
	global_atomic_add_f32 v188, v170, s[88:89]
	global_atomic_add_f32 v188, v171, s[88:89] offset:64
	global_atomic_add_f32 v188, v172, s[88:89] offset:128
	global_atomic_add_f32 v188, v173, s[88:89] offset:192
	global_atomic_add_f32 v188, v174, s[88:89] offset:512
	global_atomic_add_f32 v188, v175, s[88:89] offset:576
	global_atomic_add_f32 v188, v176, s[88:89] offset:640
	global_atomic_add_f32 v188, v177, s[88:89] offset:704
	s_mov_b64 exec, -1
	s_branch .LBB0_729
.Lepi_out_slow:
	s_lshl_b32 s6, s37, 8
	s_add_i32 s18, s6, s30
	v_or_b32_e32 v148, s18, v134
	v_cmp_lt_i32_e32 vcc, s48, v148
	s_and_saveexec_b64 s[6:7], vcc
	s_xor_b64 s[6:7], exec, s[6:7]
	s_cmpk_lt_u32 s18, 0x8820
	v_mov_b32_e32 v149, v137
	v_lshl_add_u64 v[146:147], v[148:149], 0, s[14:15]
	s_cselect_b64 vcc, -1, 0
	v_cndmask_b32_e32 v151, -1, v147, vcc
	v_cndmask_b32_e32 v150, -1, v146, vcc
	s_andn2_saveexec_b64 s[6:7], s[6:7]
	s_cbranch_execz .LBB0_742
	v_mul_hi_i32 v136, v148, s49
	v_lshrrev_b32_e32 v146, 31, v136
	v_ashrrev_i32_e32 v136, 13, v136
	v_add_u32_e32 v146, v136, v146
	v_mul_i32_i24_e32 v136, 0xffffbff0, v146
	v_add_u32_e32 v149, v136, v148
	v_ashrrev_i32_e32 v147, 31, v146
	v_lshlrev_b64 v[146:147], 14, v[146:147]
	v_add_u32_e32 v136, -16, v149
	v_lshl_add_u64 v[146:147], v[146:147], 0, v[136:137]
	v_cmp_lt_i32_e32 vcc, 15, v149
	s_nop 1
	v_cndmask_b32_e32 v151, -1, v147, vcc
	v_cndmask_b32_e32 v150, -1, v146, vcc
